# write-through epilogue stores only where the consumer is cross-XCD (in-proj Z, FFN-up H); in-proj loops peeled
# speedup vs baseline: 1.0035x; 1.0035x over previous
; __device__ __forceinline__ unsigned cvt_pk_bf16(float lo, float hi) { unsigned r; asm volatile("v_cvt_pk_bf16_f32 %0, %1, %2" : "=v"(r) : "v"(lo), "v"(hi)); return r; }
;     __device__ __forceinline__ void operator()(const f32x4 (&acc)[2][2][4][2], const Unit& u, int wr, int wc, int fr, int fq) const {
;     ...
;         const int row0 = u.pm * BM + wr * 64 + fr + (u.qa > 0 ? HALF : 0), col0 = u.pn * BM + wc * 32 + 8 * fq + (u.qb > 0 ? HALF : 0);
;         float rsv[2][4];
; #pragma unroll
;         for (int ai = 0; ai < 2; ++ai)
; #pragma unroll
;             for (int m = 0; m < 4; ++m) rsv[ai][m] = ss[row0 + ai * HALF + m * 16];
; #pragma unroll
;         for (int ai = 0; ai < 2; ++ai)
; #pragma unroll
;             for (int m = 0; m < 4; ++m) rsv[ai][m] = __builtin_amdgcn_rsqf(rsv[ai][m] * (1.0f / 1024.0f) + RMS_EPS);
; #pragma unroll
;         for (int ai = 0; ai < 2; ++ai)
; #pragma unroll
;             for (int m = 0; m < 4; ++m) {
;                 if (ai == 1 && !whole) continue;
;                 const int row = row0 + ai * HALF + m * 16;
;                 const float rs = rsv[ai][m];
;                 float s1 = 0.f, s2 = 0.f;
;                 bf16_t* rowp = BLK ? O + ((size_t)u.pm * (ldc >> 6) + (size_t)(col0 >> 6)) * 16384 + (size_t)((col0 >> 5) & 1) * 8192 + (size_t)(row - u.pm * BM) * 32 + (col0 & 31) : O + (size_t)row * ldc + col0;
; #pragma unroll
;                 for (int bj = 0; bj < 2; ++bj) {
;                     if (bj == 1 && !whole) continue;
;                     f32x4 v0 = acc[ai][bj][m][0] * rs, v1 = acc[ai][bj][m][1] * rs;
;                     if (ACT == 1) {
; #pragma unroll
;                         for (int j = 0; j < 4; ++j) { const float a = fmaxf(v0[j], 0.f), b = fmaxf(v1[j], 0.f); v0[j] = a * a; v1[j] = b * b; }
;                     }
;                     u32x4 w; w.x = cvt_pk_bf16(v0[0], v0[1]); w.y = cvt_pk_bf16(v0[2], v0[3]); w.z = cvt_pk_bf16(v1[0], v1[1]); w.w = cvt_pk_bf16(v1[2], v1[3]);
;                     *(u32x4*)(rowp + (BLK ? bj * 2 * 16384 : bj * HALF)) = w;
.LBB0_501:
	s_lshl_b32 s6, s78, 8
	v_add_u32_e32 v150, s6, v138
	v_or_b32_e32 v160, 16, v150
	v_or_b32_e32 v158, 32, v150
	v_ashrrev_i32_e32 v161, 31, v160
	v_ashrrev_i32_e32 v159, 31, v158
	v_or_b32_e32 v154, 48, v150
	v_ashrrev_i32_e32 v151, 31, v150
	v_lshl_add_u64 v[152:153], v[160:161], 2, s[42:43]
	v_lshl_add_u64 v[156:157], v[158:159], 2, s[42:43]
	v_ashrrev_i32_e32 v155, 31, v154
	v_lshl_add_u64 v[150:151], v[150:151], 2, s[42:43]
	v_lshl_add_u64 v[162:163], v[154:155], 2, s[42:43]
	global_load_dword v146, v[150:151], off offset:512
	global_load_dword v148, v[150:151], off offset:576
	global_load_dword v155, v[150:151], off offset:640
	global_load_dword v159, v[150:151], off offset:704
	s_nop 0
	global_load_dword v152, v[152:153], off
	s_nop 0
	global_load_dword v153, v[156:157], off
	s_nop 0
	global_load_dword v156, v[162:163], off
	global_load_dword v157, v[150:151], off
	s_lshl_b32 s4, s18, 8
	s_or_b32 s7, s4, s96
	s_ashr_i32 s18, s7, 6
	s_ashr_i32 s79, s78, 31
	s_ashr_i32 s19, s18, 31
	s_lshl_b64 s[4:5], s[78:79], 21
	s_lshl_b64 s[18:19], s[18:19], 15
	s_add_u32 s4, s34, s4
	s_addc_u32 s5, s35, s5
	s_add_u32 s4, s4, s18
	s_addc_u32 s5, s5, s19
	s_add_u32 s4, s4, s16
	s_addc_u32 s5, s5, 0
	v_lshl_add_u64 v[150:151], s[4:5], 0, v[140:141]
	v_lshl_add_u64 v[162:163], v[150:151], 0, v[136:137]
	s_waitcnt vmcnt(0)
	v_fmamk_f32 v146, v146, 0x3a800000, v149
	v_fmamk_f32 v148, v148, 0x3a800000, v149
	v_fmamk_f32 v151, v155, 0x3a800000, v149
	v_rsq_f32_e32 v150, v148
	v_rsq_f32_e32 v148, v151
	v_fmamk_f32 v155, v159, 0x3a800000, v149
	v_fmamk_f32 v159, v152, 0x3a800000, v149
	v_fmamk_f32 v151, v157, 0x3a800000, v149
	v_rsq_f32_e32 v164, v151
	v_rsq_f32_e32 v166, v159
	v_fmamk_f32 v153, v153, 0x3a800000, v149
	v_rsq_f32_e32 v152, v146
	v_pk_mul_f32 v[126:127], v[126:127], v[164:165] op_sel_hi:[1,0]
	v_pk_mul_f32 v[124:125], v[124:125], v[164:165] op_sel_hi:[1,0]
	v_pk_mul_f32 v[116:117], v[116:117], v[164:165] op_sel_hi:[1,0]
	v_pk_mul_f32 v[112:113], v[112:113], v[164:165] op_sel_hi:[1,0]
	v_pk_mul_f32 v[122:123], v[122:123], v[164:165] op_sel_hi:[1,0]
	v_pk_mul_f32 v[120:121], v[120:121], v[164:165] op_sel_hi:[1,0]
	v_pk_mul_f32 v[114:115], v[114:115], v[164:165] op_sel_hi:[1,0]
	v_max_f32_e32 v124, 0, v124
	v_max_f32_e32 v125, 0, v125
	v_max_f32_e32 v126, 0, v126
	v_max_f32_e32 v127, 0, v127
	v_max_f32_e32 v116, 0, v116
	v_max_f32_e32 v112, 0, v112
	v_pk_mul_f32 v[118:119], v[118:119], v[164:165] op_sel_hi:[1,0]
	v_max_f32_e32 v120, 0, v120
	v_max_f32_e32 v121, 0, v121
	v_max_f32_e32 v122, 0, v122
	v_max_f32_e32 v123, 0, v123
	v_max_f32_e32 v117, 0, v117
	v_max_f32_e32 v113, 0, v113
	v_max_f32_e32 v114, 0, v114
	v_max_f32_e32 v151, 0, v115
	v_mul_f32_e32 v115, v124, v124
	v_mul_f32_e32 v124, v125, v125
	v_mul_f32_e32 v125, v126, v126
	v_mul_f32_e32 v126, v127, v127
	v_mul_f32_e32 v116, v116, v116
	v_mul_f32_e32 v127, v112, v112
	v_cvt_pk_bf16_f32 v112, v115, v124
	v_rsq_f32_e32 v146, v155
	v_rsq_f32_e32 v168, v153
	v_max_f32_e32 v119, 0, v119
	v_mul_f32_e32 v120, v120, v120
	v_mul_f32_e32 v121, v121, v121
	v_mul_f32_e32 v122, v122, v122
	v_mul_f32_e32 v123, v123, v123
	v_mul_f32_e32 v117, v117, v117
	v_mul_f32_e32 v153, v113, v113
	v_mul_f32_e32 v155, v114, v114
	v_cvt_pk_bf16_f32 v113, v125, v126
	v_cvt_pk_bf16_f32 v114, v120, v121
	v_cvt_pk_bf16_f32 v115, v122, v123
	global_store_dwordx4 v[162:163], v[112:115], off sc1
	v_max_f32_e32 v118, 0, v118
	v_mul_f32_e32 v118, v118, v118
	v_cvt_pk_bf16_f32 v112, v116, v117
	v_add_co_u32_e32 v116, vcc, s95, v162
	v_mul_f32_e32 v113, v119, v119
	v_mul_f32_e32 v115, v151, v151
	v_addc_co_u32_e32 v117, vcc, 0, v163, vcc
	v_cvt_pk_bf16_f32 v113, v118, v113
	v_cvt_pk_bf16_f32 v114, v127, v153
	v_cvt_pk_bf16_f32 v115, v155, v115
	global_store_dwordx4 v[116:117], v[112:115], off sc1
	v_pk_mul_f32 v[104:105], v[104:105], v[166:167] op_sel_hi:[1,0]
	v_pk_mul_f32 v[108:109], v[108:109], v[166:167] op_sel_hi:[1,0]
	v_subrev_u32_e32 v112, s6, v160
	v_ashrrev_i32_e32 v113, 31, v112
	v_pk_mul_f32 v[106:107], v[106:107], v[166:167] op_sel_hi:[1,0]
	v_max_f32_e32 v104, 0, v104
	v_lshlrev_b64 v[112:113], 6, v[112:113]
	v_pk_mul_f32 v[110:111], v[110:111], v[166:167] op_sel_hi:[1,0]
	v_mul_f32_e32 v114, v104, v104
	v_max_f32_e32 v104, 0, v109
	v_max_f32_e32 v105, 0, v105
	v_max_f32_e32 v106, 0, v106
	v_lshl_add_u64 v[112:113], s[4:5], 0, v[112:113]
	v_max_f32_e32 v108, 0, v108
	v_mul_f32_e32 v104, v104, v104
	v_mul_f32_e32 v109, v105, v105
	v_max_f32_e32 v105, 0, v110
	v_mul_f32_e32 v110, v106, v106
	v_max_f32_e32 v106, 0, v111
	v_max_f32_e32 v107, 0, v107
	v_pk_mul_f32 v[96:97], v[96:97], v[166:167] op_sel_hi:[1,0]
	v_lshl_add_u64 v[112:113], v[112:113], 0, v[136:137]
	v_mul_f32_e32 v108, v108, v108
	v_mul_f32_e32 v105, v105, v105
	v_mul_f32_e32 v106, v106, v106
	v_mul_f32_e32 v107, v107, v107
	v_cvt_pk_bf16_f32 v104, v108, v104
	v_pk_mul_f32 v[100:101], v[100:101], v[166:167] op_sel_hi:[1,0]
	v_pk_mul_f32 v[98:99], v[98:99], v[166:167] op_sel_hi:[1,0]
	v_max_f32_e32 v96, 0, v96
	v_cvt_pk_bf16_f32 v105, v105, v106
	v_cvt_pk_bf16_f32 v106, v114, v109
	v_cvt_pk_bf16_f32 v107, v110, v107
	global_store_dwordx4 v[112:113], v[104:107], off sc1
	v_pk_mul_f32 v[102:103], v[102:103], v[166:167] op_sel_hi:[1,0]
	v_max_f32_e32 v100, 0, v100
	v_mul_f32_e32 v104, v96, v96
	v_max_f32_e32 v96, 0, v101
	v_max_f32_e32 v97, 0, v97
	v_max_f32_e32 v98, 0, v98
	v_mul_f32_e32 v100, v100, v100
	v_mul_f32_e32 v96, v96, v96
	v_mul_f32_e32 v101, v97, v97
	v_max_f32_e32 v97, 0, v102
	v_mul_f32_e32 v102, v98, v98
	v_max_f32_e32 v98, 0, v103
	v_mul_f32_e32 v97, v97, v97
	v_max_f32_e32 v99, 0, v99
	v_mul_f32_e32 v98, v98, v98
; __device__ __forceinline__ unsigned cvt_pk_bf16(float lo, float hi) { unsigned r; asm volatile("v_cvt_pk_bf16_f32 %0, %1, %2" : "=v"(r) : "v"(lo), "v"(hi)); return r; }
;     __device__ __forceinline__ void operator()(const f32x4 (&acc)[2][2][4][2], const Unit& u, int wr, int wc, int fr, int fq) const {
;     ...
;         for (int ai = 0; ai < 2; ++ai)
; #pragma unroll
;             for (int m = 0; m < 4; ++m) {
;                 if (ai == 1 && !whole) continue;
;                 const int row = row0 + ai * HALF + m * 16;
;                 const float rs = rsv[ai][m];
;                 float s1 = 0.f, s2 = 0.f;
;                 bf16_t* rowp = BLK ? O + ((size_t)u.pm * (ldc >> 6) + (size_t)(col0 >> 6)) * 16384 + (size_t)((col0 >> 5) & 1) * 8192 + (size_t)(row - u.pm * BM) * 32 + (col0 & 31) : O + (size_t)row * ldc + col0;
; #pragma unroll
;                 for (int bj = 0; bj < 2; ++bj) {
;                     if (bj == 1 && !whole) continue;
;                     f32x4 v0 = acc[ai][bj][m][0] * rs, v1 = acc[ai][bj][m][1] * rs;
;                     if (ACT == 1) {
; #pragma unroll
;                         for (int j = 0; j < 4; ++j) { const float a = fmaxf(v0[j], 0.f), b = fmaxf(v1[j], 0.f); v0[j] = a * a; v1[j] = b * b; }
;                     }
;                     u32x4 w; w.x = cvt_pk_bf16(v0[0], v0[1]); w.y = cvt_pk_bf16(v0[2], v0[3]); w.z = cvt_pk_bf16(v1[0], v1[1]); w.w = cvt_pk_bf16(v1[2], v1[3]);
;                     *(u32x4*)(rowp + (BLK ? bj * 2 * 16384 : bj * HALF)) = w;
	v_cvt_pk_bf16_f32 v96, v100, v96
	v_add_co_u32_e32 v100, vcc, s95, v112
	v_mul_f32_e32 v99, v99, v99
	v_cvt_pk_bf16_f32 v97, v97, v98
	v_cvt_pk_bf16_f32 v98, v104, v101
	s_nop 0
	v_addc_co_u32_e32 v101, vcc, 0, v113, vcc
	v_cvt_pk_bf16_f32 v99, v102, v99
	global_store_dwordx4 v[100:101], v[96:99], off sc1
	v_pk_mul_f32 v[88:89], v[88:89], v[168:169] op_sel_hi:[1,0]
	v_pk_mul_f32 v[92:93], v[92:93], v[168:169] op_sel_hi:[1,0]
	v_subrev_u32_e32 v96, s6, v158
	v_ashrrev_i32_e32 v97, 31, v96
	v_pk_mul_f32 v[90:91], v[90:91], v[168:169] op_sel_hi:[1,0]
	v_max_f32_e32 v88, 0, v88
	v_lshlrev_b64 v[96:97], 6, v[96:97]
	v_pk_mul_f32 v[94:95], v[94:95], v[168:169] op_sel_hi:[1,0]
	v_mul_f32_e32 v98, v88, v88
	v_max_f32_e32 v88, 0, v93
	v_max_f32_e32 v89, 0, v89
	v_max_f32_e32 v90, 0, v90
	v_lshl_add_u64 v[96:97], s[4:5], 0, v[96:97]
	v_max_f32_e32 v92, 0, v92
	v_mul_f32_e32 v88, v88, v88
	v_mul_f32_e32 v93, v89, v89
	v_max_f32_e32 v89, 0, v94
	v_mul_f32_e32 v94, v90, v90
	v_max_f32_e32 v90, 0, v95
	v_max_f32_e32 v91, 0, v91
	v_pk_mul_f32 v[80:81], v[80:81], v[168:169] op_sel_hi:[1,0]
	v_fmamk_f32 v156, v156, 0x3a800000, v149
	v_lshl_add_u64 v[96:97], v[96:97], 0, v[136:137]
	v_mul_f32_e32 v92, v92, v92
	v_mul_f32_e32 v89, v89, v89
	v_mul_f32_e32 v90, v90, v90
	v_mul_f32_e32 v91, v91, v91
	v_cvt_pk_bf16_f32 v88, v92, v88
	v_pk_mul_f32 v[84:85], v[84:85], v[168:169] op_sel_hi:[1,0]
	v_pk_mul_f32 v[82:83], v[82:83], v[168:169] op_sel_hi:[1,0]
	v_max_f32_e32 v80, 0, v80
	v_rsq_f32_e32 v156, v156
	v_cvt_pk_bf16_f32 v89, v89, v90
	v_cvt_pk_bf16_f32 v90, v98, v93
	v_cvt_pk_bf16_f32 v91, v94, v91
	global_store_dwordx4 v[96:97], v[88:91], off sc1
	v_pk_mul_f32 v[86:87], v[86:87], v[168:169] op_sel_hi:[1,0]
	v_max_f32_e32 v84, 0, v84
	v_mul_f32_e32 v88, v80, v80
	v_max_f32_e32 v80, 0, v85
	v_max_f32_e32 v81, 0, v81
	v_max_f32_e32 v82, 0, v82
	v_mul_f32_e32 v84, v84, v84
	v_mul_f32_e32 v80, v80, v80
	v_mul_f32_e32 v85, v81, v81
	v_max_f32_e32 v81, 0, v86
	v_mul_f32_e32 v86, v82, v82
	v_max_f32_e32 v82, 0, v87
	v_mul_f32_e32 v81, v81, v81
	v_max_f32_e32 v83, 0, v83
	v_mul_f32_e32 v82, v82, v82
	v_cvt_pk_bf16_f32 v80, v84, v80
	v_add_co_u32_e32 v84, vcc, s95, v96
	v_mul_f32_e32 v83, v83, v83
	v_cvt_pk_bf16_f32 v81, v81, v82
	v_cvt_pk_bf16_f32 v82, v88, v85
	s_nop 0
	v_addc_co_u32_e32 v85, vcc, 0, v97, vcc
	v_cvt_pk_bf16_f32 v83, v86, v83
	global_store_dwordx4 v[84:85], v[80:83], off sc1
	v_pk_mul_f32 v[72:73], v[72:73], v[156:157] op_sel_hi:[1,0]
	v_pk_mul_f32 v[76:77], v[76:77], v[156:157] op_sel_hi:[1,0]
	v_subrev_u32_e32 v80, s6, v154
	v_ashrrev_i32_e32 v81, 31, v80
	v_pk_mul_f32 v[74:75], v[74:75], v[156:157] op_sel_hi:[1,0]
	v_max_f32_e32 v72, 0, v72
	v_lshlrev_b64 v[80:81], 6, v[80:81]
	v_pk_mul_f32 v[78:79], v[78:79], v[156:157] op_sel_hi:[1,0]
	v_mul_f32_e32 v82, v72, v72
	v_max_f32_e32 v72, 0, v77
	v_max_f32_e32 v73, 0, v73
	v_max_f32_e32 v74, 0, v74
	v_lshl_add_u64 v[80:81], s[4:5], 0, v[80:81]
	v_max_f32_e32 v76, 0, v76
	v_mul_f32_e32 v72, v72, v72
	v_mul_f32_e32 v77, v73, v73
	v_max_f32_e32 v73, 0, v78
	v_mul_f32_e32 v78, v74, v74
	v_max_f32_e32 v74, 0, v79
	v_max_f32_e32 v75, 0, v75
	v_pk_mul_f32 v[64:65], v[64:65], v[156:157] op_sel_hi:[1,0]
	v_lshl_add_u64 v[80:81], v[80:81], 0, v[136:137]
	v_mul_f32_e32 v76, v76, v76
	v_mul_f32_e32 v73, v73, v73
	v_mul_f32_e32 v74, v74, v74
	v_mul_f32_e32 v75, v75, v75
	v_cvt_pk_bf16_f32 v72, v76, v72
	v_pk_mul_f32 v[68:69], v[68:69], v[156:157] op_sel_hi:[1,0]
	v_pk_mul_f32 v[66:67], v[66:67], v[156:157] op_sel_hi:[1,0]
	v_max_f32_e32 v64, 0, v64
	v_cvt_pk_bf16_f32 v73, v73, v74
	v_cvt_pk_bf16_f32 v74, v82, v77
	v_cvt_pk_bf16_f32 v75, v78, v75
	global_store_dwordx4 v[80:81], v[72:75], off sc1
	v_pk_mul_f32 v[70:71], v[70:71], v[156:157] op_sel_hi:[1,0]
	v_max_f32_e32 v68, 0, v68
	v_mul_f32_e32 v72, v64, v64
	v_max_f32_e32 v64, 0, v69
	v_max_f32_e32 v65, 0, v65
	v_max_f32_e32 v66, 0, v66
	v_mul_f32_e32 v68, v68, v68
	v_mul_f32_e32 v64, v64, v64
	v_mul_f32_e32 v69, v65, v65
	v_max_f32_e32 v65, 0, v70
	v_mul_f32_e32 v70, v66, v66
	v_max_f32_e32 v66, 0, v71
	v_mul_f32_e32 v65, v65, v65
	v_max_f32_e32 v67, 0, v67
	v_mul_f32_e32 v66, v66, v66
	v_cvt_pk_bf16_f32 v64, v68, v64
	v_add_co_u32_e32 v68, vcc, s95, v80
	v_mul_f32_e32 v67, v67, v67
	v_cvt_pk_bf16_f32 v65, v65, v66
	v_cvt_pk_bf16_f32 v66, v72, v69
	s_nop 0
	v_addc_co_u32_e32 v69, vcc, 0, v81, vcc
	v_cvt_pk_bf16_f32 v67, v70, v67
	global_store_dwordx4 v[68:69], v[64:67], off sc1
	v_pk_mul_f32 v[56:57], v[56:57], v[152:153] op_sel_hi:[1,0]
	v_pk_mul_f32 v[60:61], v[60:61], v[152:153] op_sel_hi:[1,0]
	v_add_u32_e32 v64, 0x80, v138
	v_ashrrev_i32_e32 v65, 31, v64
	v_pk_mul_f32 v[58:59], v[58:59], v[152:153] op_sel_hi:[1,0]
	v_max_f32_e32 v56, 0, v56
	v_lshlrev_b64 v[64:65], 6, v[64:65]
	v_pk_mul_f32 v[62:63], v[62:63], v[152:153] op_sel_hi:[1,0]
	v_mul_f32_e32 v66, v56, v56
	v_max_f32_e32 v56, 0, v61
	v_max_f32_e32 v57, 0, v57
	v_max_f32_e32 v58, 0, v58
	v_lshl_add_u64 v[64:65], s[4:5], 0, v[64:65]
	v_max_f32_e32 v60, 0, v60
	v_mul_f32_e32 v56, v56, v56
	v_mul_f32_e32 v61, v57, v57
	v_max_f32_e32 v57, 0, v62
	v_mul_f32_e32 v62, v58, v58
	v_max_f32_e32 v58, 0, v63
	v_max_f32_e32 v59, 0, v59
	v_pk_mul_f32 v[48:49], v[48:49], v[152:153] op_sel_hi:[1,0]
	v_lshl_add_u64 v[64:65], v[64:65], 0, v[136:137]
	v_mul_f32_e32 v60, v60, v60
	v_mul_f32_e32 v57, v57, v57
	v_mul_f32_e32 v58, v58, v58
	v_mul_f32_e32 v59, v59, v59
	v_cvt_pk_bf16_f32 v56, v60, v56
	v_pk_mul_f32 v[52:53], v[52:53], v[152:153] op_sel_hi:[1,0]
	v_pk_mul_f32 v[50:51], v[50:51], v[152:153] op_sel_hi:[1,0]
	v_max_f32_e32 v48, 0, v48
	v_cvt_pk_bf16_f32 v57, v57, v58
	v_cvt_pk_bf16_f32 v58, v66, v61
; __device__ __forceinline__ unsigned cvt_pk_bf16(float lo, float hi) { unsigned r; asm volatile("v_cvt_pk_bf16_f32 %0, %1, %2" : "=v"(r) : "v"(lo), "v"(hi)); return r; }
; #define PG8_BAR __builtin_amdgcn_s_barrier()
;     __device__ __forceinline__ void operator()(const f32x4 (&acc)[2][2][4][2], const Unit& u, int wr, int wc, int fr, int fq) const {
;     ...
;         for (int ai = 0; ai < 2; ++ai)
; #pragma unroll
;             for (int m = 0; m < 4; ++m) {
;                 if (ai == 1 && !whole) continue;
;                 const int row = row0 + ai * HALF + m * 16;
;                 const float rs = rsv[ai][m];
;                 float s1 = 0.f, s2 = 0.f;
;                 bf16_t* rowp = BLK ? O + ((size_t)u.pm * (ldc >> 6) + (size_t)(col0 >> 6)) * 16384 + (size_t)((col0 >> 5) & 1) * 8192 + (size_t)(row - u.pm * BM) * 32 + (col0 & 31) : O + (size_t)row * ldc + col0;
; #pragma unroll
;                 for (int bj = 0; bj < 2; ++bj) {
;                     if (bj == 1 && !whole) continue;
;                     f32x4 v0 = acc[ai][bj][m][0] * rs, v1 = acc[ai][bj][m][1] * rs;
;                     if (ACT == 1) {
; #pragma unroll
;                         for (int j = 0; j < 4; ++j) { const float a = fmaxf(v0[j], 0.f), b = fmaxf(v1[j], 0.f); v0[j] = a * a; v1[j] = b * b; }
;                     }
;                     u32x4 w; w.x = cvt_pk_bf16(v0[0], v0[1]); w.y = cvt_pk_bf16(v0[2], v0[3]); w.z = cvt_pk_bf16(v1[0], v1[1]); w.w = cvt_pk_bf16(v1[2], v1[3]);
;                     *(u32x4*)(rowp + (BLK ? bj * 2 * 16384 : bj * HALF)) = w;
; template <class Epi, class Sched, bool ALIGN_EPI = false, bool SP2 = false>
; __device__ __forceinline__ void gemm_phase(PG8_LAS unsigned char* lds, const Gemm g, const Sched& S, const Epi& E) {
;     ...
;         if constexpr (ALIGN_EPI) { if (wr == 0) PG8_BAR; }
;         if constexpr (!Epi::AFTER_DRAIN) { E(acc, cur, wr, wc, fr, fq); S.done(cur); }
;         if (!has_next) break;
; #pragma unroll
;         for (int a = 0; a < 2; ++a)
; #pragma unroll
;             for (int b = 0; b < 2; ++b)
; #pragma unroll
;                 for (int m = 0; m < 4; ++m)
; #pragma unroll
;                     for (int n = 0; n < 2; ++n) acc[a][b][m][n] = (f32x4){0.f, 0.f, 0.f, 0.f};
;         cur = nxt; cA = nA; cB = nB; ++ui;
;         if constexpr (ALIGN_EPI) { if (wr == 1) PG8_BAR; }
	v_cvt_pk_bf16_f32 v59, v62, v59
	global_store_dwordx4 v[64:65], v[56:59], off sc1
	v_pk_mul_f32 v[54:55], v[54:55], v[152:153] op_sel_hi:[1,0]
	v_max_f32_e32 v52, 0, v52
	v_mul_f32_e32 v56, v48, v48
	v_max_f32_e32 v48, 0, v53
	v_max_f32_e32 v49, 0, v49
	v_max_f32_e32 v50, 0, v50
	v_mul_f32_e32 v52, v52, v52
	v_mul_f32_e32 v48, v48, v48
	v_mul_f32_e32 v53, v49, v49
	v_max_f32_e32 v49, 0, v54
	v_mul_f32_e32 v54, v50, v50
	v_max_f32_e32 v50, 0, v55
	v_mul_f32_e32 v49, v49, v49
	v_max_f32_e32 v51, 0, v51
	v_mul_f32_e32 v50, v50, v50
	v_cvt_pk_bf16_f32 v48, v52, v48
	v_add_co_u32_e32 v52, vcc, s95, v64
	v_mul_f32_e32 v51, v51, v51
	v_cvt_pk_bf16_f32 v49, v49, v50
	v_cvt_pk_bf16_f32 v50, v56, v53
	s_nop 0
	v_addc_co_u32_e32 v53, vcc, 0, v65, vcc
	v_cvt_pk_bf16_f32 v51, v54, v51
	global_store_dwordx4 v[52:53], v[48:51], off sc1
	v_pk_mul_f32 v[40:41], v[40:41], v[150:151] op_sel_hi:[1,0]
	v_pk_mul_f32 v[44:45], v[44:45], v[150:151] op_sel_hi:[1,0]
	v_add_u32_e32 v48, 0x90, v138
	v_ashrrev_i32_e32 v49, 31, v48
	v_pk_mul_f32 v[42:43], v[42:43], v[150:151] op_sel_hi:[1,0]
	v_max_f32_e32 v40, 0, v40
	v_lshlrev_b64 v[48:49], 6, v[48:49]
	v_pk_mul_f32 v[46:47], v[46:47], v[150:151] op_sel_hi:[1,0]
	v_mul_f32_e32 v50, v40, v40
	v_max_f32_e32 v40, 0, v45
	v_max_f32_e32 v41, 0, v41
	v_max_f32_e32 v42, 0, v42
	v_lshl_add_u64 v[48:49], s[4:5], 0, v[48:49]
	v_max_f32_e32 v44, 0, v44
	v_mul_f32_e32 v40, v40, v40
	v_mul_f32_e32 v45, v41, v41
	v_max_f32_e32 v41, 0, v46
	v_mul_f32_e32 v46, v42, v42
	v_max_f32_e32 v42, 0, v47
	v_max_f32_e32 v43, 0, v43
	v_pk_mul_f32 v[32:33], v[32:33], v[150:151] op_sel_hi:[1,0]
	v_lshl_add_u64 v[48:49], v[48:49], 0, v[136:137]
	v_mul_f32_e32 v44, v44, v44
	v_mul_f32_e32 v41, v41, v41
	v_mul_f32_e32 v42, v42, v42
	v_mul_f32_e32 v43, v43, v43
	v_cvt_pk_bf16_f32 v40, v44, v40
	v_pk_mul_f32 v[36:37], v[36:37], v[150:151] op_sel_hi:[1,0]
	v_pk_mul_f32 v[34:35], v[34:35], v[150:151] op_sel_hi:[1,0]
	v_max_f32_e32 v32, 0, v32
	v_cvt_pk_bf16_f32 v41, v41, v42
	v_cvt_pk_bf16_f32 v42, v50, v45
	v_cvt_pk_bf16_f32 v43, v46, v43
	global_store_dwordx4 v[48:49], v[40:43], off sc1
	v_pk_mul_f32 v[38:39], v[38:39], v[150:151] op_sel_hi:[1,0]
	v_max_f32_e32 v36, 0, v36
	v_mul_f32_e32 v40, v32, v32
	v_max_f32_e32 v32, 0, v37
	v_max_f32_e32 v33, 0, v33
	v_max_f32_e32 v34, 0, v34
	v_mul_f32_e32 v36, v36, v36
	v_mul_f32_e32 v32, v32, v32
	v_mul_f32_e32 v37, v33, v33
	v_max_f32_e32 v33, 0, v38
	v_mul_f32_e32 v38, v34, v34
	v_max_f32_e32 v34, 0, v39
	v_mul_f32_e32 v33, v33, v33
	v_max_f32_e32 v35, 0, v35
	v_mul_f32_e32 v34, v34, v34
	v_cvt_pk_bf16_f32 v32, v36, v32
	v_add_co_u32_e32 v36, vcc, s95, v48
	v_mul_f32_e32 v35, v35, v35
	v_cvt_pk_bf16_f32 v33, v33, v34
	v_cvt_pk_bf16_f32 v34, v40, v37
	s_nop 0
	v_addc_co_u32_e32 v37, vcc, 0, v49, vcc
	v_cvt_pk_bf16_f32 v35, v38, v35
	global_store_dwordx4 v[36:37], v[32:35], off sc1
	v_pk_mul_f32 v[24:25], v[24:25], v[148:149] op_sel_hi:[1,0]
	v_pk_mul_f32 v[28:29], v[28:29], v[148:149] op_sel_hi:[1,0]
	v_add_u32_e32 v32, 0xa0, v138
	v_ashrrev_i32_e32 v33, 31, v32
	v_pk_mul_f32 v[26:27], v[26:27], v[148:149] op_sel_hi:[1,0]
	v_max_f32_e32 v24, 0, v24
	v_lshlrev_b64 v[32:33], 6, v[32:33]
	v_pk_mul_f32 v[30:31], v[30:31], v[148:149] op_sel_hi:[1,0]
	v_mul_f32_e32 v34, v24, v24
	v_max_f32_e32 v24, 0, v29
	v_max_f32_e32 v25, 0, v25
	v_max_f32_e32 v26, 0, v26
	v_lshl_add_u64 v[32:33], s[4:5], 0, v[32:33]
	v_max_f32_e32 v28, 0, v28
	v_mul_f32_e32 v24, v24, v24
	v_mul_f32_e32 v29, v25, v25
	v_max_f32_e32 v25, 0, v30
	v_mul_f32_e32 v30, v26, v26
	v_max_f32_e32 v26, 0, v31
	v_max_f32_e32 v27, 0, v27
	v_pk_mul_f32 v[16:17], v[16:17], v[148:149] op_sel_hi:[1,0]
	v_lshl_add_u64 v[32:33], v[32:33], 0, v[136:137]
	v_mul_f32_e32 v28, v28, v28
	v_mul_f32_e32 v25, v25, v25
	v_mul_f32_e32 v26, v26, v26
	v_mul_f32_e32 v27, v27, v27
	v_cvt_pk_bf16_f32 v24, v28, v24
	v_pk_mul_f32 v[20:21], v[20:21], v[148:149] op_sel_hi:[1,0]
	v_pk_mul_f32 v[18:19], v[18:19], v[148:149] op_sel_hi:[1,0]
	v_max_f32_e32 v16, 0, v16
	v_cvt_pk_bf16_f32 v25, v25, v26
	v_cvt_pk_bf16_f32 v26, v34, v29
	v_cvt_pk_bf16_f32 v27, v30, v27
	global_store_dwordx4 v[32:33], v[24:27], off sc1
	v_pk_mul_f32 v[22:23], v[22:23], v[148:149] op_sel_hi:[1,0]
	v_max_f32_e32 v20, 0, v20
	v_mul_f32_e32 v24, v16, v16
	v_max_f32_e32 v16, 0, v21
	v_max_f32_e32 v17, 0, v17
	v_max_f32_e32 v18, 0, v18
	v_mul_f32_e32 v20, v20, v20
	v_mul_f32_e32 v16, v16, v16
	v_mul_f32_e32 v21, v17, v17
	v_max_f32_e32 v17, 0, v22
	v_mul_f32_e32 v22, v18, v18
	v_max_f32_e32 v18, 0, v23
	v_mul_f32_e32 v17, v17, v17
	v_max_f32_e32 v19, 0, v19
	v_mul_f32_e32 v18, v18, v18
	v_cvt_pk_bf16_f32 v16, v20, v16
	v_add_co_u32_e32 v20, vcc, s95, v32
	v_mul_f32_e32 v19, v19, v19
	v_cvt_pk_bf16_f32 v17, v17, v18
	v_cvt_pk_bf16_f32 v18, v24, v21
	s_nop 0
	v_addc_co_u32_e32 v21, vcc, 0, v33, vcc
	v_cvt_pk_bf16_f32 v19, v22, v19
	global_store_dwordx4 v[20:21], v[16:19], off sc1
	v_pk_mul_f32 v[8:9], v[8:9], v[146:147] op_sel_hi:[1,0]
	v_pk_mul_f32 v[12:13], v[12:13], v[146:147] op_sel_hi:[1,0]
	v_add_u32_e32 v16, 0xb0, v138
	v_ashrrev_i32_e32 v17, 31, v16
	v_pk_mul_f32 v[10:11], v[10:11], v[146:147] op_sel_hi:[1,0]
	v_max_f32_e32 v8, 0, v8
	v_lshlrev_b64 v[16:17], 6, v[16:17]
	v_pk_mul_f32 v[14:15], v[14:15], v[146:147] op_sel_hi:[1,0]
	v_mul_f32_e32 v18, v8, v8
	v_max_f32_e32 v8, 0, v13
	v_max_f32_e32 v9, 0, v9
	v_max_f32_e32 v10, 0, v10
	v_lshl_add_u64 v[16:17], s[4:5], 0, v[16:17]
	v_max_f32_e32 v12, 0, v12
	v_mul_f32_e32 v8, v8, v8
	v_mul_f32_e32 v13, v9, v9
	v_max_f32_e32 v9, 0, v14
	v_mul_f32_e32 v14, v10, v10
	v_max_f32_e32 v10, 0, v15
	v_max_f32_e32 v11, 0, v11
	v_pk_mul_f32 v[0:1], v[0:1], v[146:147] op_sel_hi:[1,0]
	v_lshl_add_u64 v[16:17], v[16:17], 0, v[136:137]
	v_mul_f32_e32 v12, v12, v12
	v_mul_f32_e32 v9, v9, v9
	v_mul_f32_e32 v10, v10, v10
	v_mul_f32_e32 v11, v11, v11
	v_cvt_pk_bf16_f32 v8, v12, v8
	v_pk_mul_f32 v[4:5], v[4:5], v[146:147] op_sel_hi:[1,0]
	v_pk_mul_f32 v[2:3], v[2:3], v[146:147] op_sel_hi:[1,0]
	v_max_f32_e32 v0, 0, v0
	v_cvt_pk_bf16_f32 v9, v9, v10
	v_cvt_pk_bf16_f32 v10, v18, v13
	v_cvt_pk_bf16_f32 v11, v14, v11
	global_store_dwordx4 v[16:17], v[8:11], off sc1
	v_pk_mul_f32 v[6:7], v[6:7], v[146:147] op_sel_hi:[1,0]
	v_max_f32_e32 v4, 0, v4
	v_mul_f32_e32 v8, v0, v0
	v_max_f32_e32 v0, 0, v5
	v_max_f32_e32 v1, 0, v1
	v_max_f32_e32 v2, 0, v2
	v_mul_f32_e32 v4, v4, v4
	v_mul_f32_e32 v0, v0, v0
	v_mul_f32_e32 v5, v1, v1
	v_max_f32_e32 v1, 0, v6
	v_mul_f32_e32 v6, v2, v2
	v_max_f32_e32 v2, 0, v7
	v_mul_f32_e32 v1, v1, v1
	v_mul_f32_e32 v2, v2, v2
	v_cvt_pk_bf16_f32 v0, v4, v0
	v_add_co_u32_e32 v4, vcc, 0x10000, v16
	v_max_f32_e32 v3, 0, v3
	v_cvt_pk_bf16_f32 v1, v1, v2
	v_cvt_pk_bf16_f32 v2, v8, v5
	s_nop 0
	v_addc_co_u32_e32 v5, vcc, 0, v17, vcc
	v_mul_f32_e32 v3, v3, v3
	s_andn2_b64 vcc, exec, s[2:3]
	s_mov_b64 s[2:3], -1
	v_cvt_pk_bf16_f32 v3, v6, v3
	global_store_dwordx4 v[4:5], v[0:3], off sc1
	s_cbranch_vccnz .LBB0_486
	s_andn2_b64 vcc, exec, s[54:55]
	s_cbranch_vccnz .LBB0_485
	s_barrier
	s_branch .LBB0_485

; #define LAS __attribute__((address_space(3)))
; __host__ __device__ __forceinline__ int gate_row(int n) { if (n < 512) return n; const int base = n < 1536 ? 512 : 1536, q = n - base, h = q >> 9, t = (q & 511) >> 7, r = q & 127; return base + t * 256 + h * 128 + r; }
; template <bool GATEMAP = false>
; __device__ __forceinline__ void p0_transpose_item(const float* W, int N, bf16* WT, int ldwt, int koff, const float* gain, LAS float* scr, int item, int lane) {
;     const int nblk = N / 64, kb = item / nblk, nb = item % nblk, k0 = 64 * kb, n0 = 64 * nb; const int nd0 = GATEMAP ? gate_row(n0) : n0;
;     const int ks = lane >> 4, n4 = (lane & 15) * 4;
;     f32x4 v[16];
; #pragma unroll
;     for (int i = 0; i < 16; ++i) v[i] = *(const f32x4*)(W + (size_t)(k0 + 4 * i + ks) * N + n0 + n4);
;     if (gain) {
; #pragma unroll
;         for (int i = 0; i < 16; ++i) v[i] = v[i] * gain[k0 + 4 * i + ks];
;     }
; #pragma unroll
;     for (int i = 0; i < 16; ++i) { LAS float* d = scr + (4 * i + ks) * 65 + n4; d[0] = v[i][0]; d[1] = v[i][1]; d[2] = v[i][2]; d[3] = v[i][3]; }
;     asm volatile("s_waitcnt lgkmcnt(0)" ::: "memory");
;     const int c = lane & 7;
; #pragma unroll
; template <int PART>
; __device__ __forceinline__ void phase_prologue_late(const Params& p, LAS unsigned char* lds, int cu0) {
;     ...
;     for (int it = gw; it < I_W2; it += NGW) p0_transpose_item(p.in[23], D, (bf16*)(ws + WS_W2_0), FF, 0, nullptr, scr, it, lane);
.LBB0_508:
	s_ashr_i32 s0, s13, 31
	s_lshr_b32 s0, s0, 28
	s_add_i32 s0, s13, s0
	s_ashr_i32 s0, s0, 4
	s_lshl_b32 s2, s0, 6
	s_lshl_b32 s0, s0, 10
	v_or_b32_e32 v46, s2, v8
	s_sub_i32 s0, s4, s0
	v_or_b32_e32 v48, 4, v46
	v_or_b32_e32 v50, 8, v46
	v_or_b32_e32 v52, 12, v46
	v_or_b32_e32 v54, 16, v46
	v_or_b32_e32 v56, 20, v46
	v_or_b32_e32 v58, 24, v46
	v_or_b32_e32 v60, 28, v46
	v_or_b32_e32 v62, 32, v46
	v_or_b32_e32 v64, 36, v46
	v_or_b32_e32 v66, 40, v46
	v_or_b32_e32 v68, 44, v46
	v_or_b32_e32 v70, 48, v46
	v_or_b32_e32 v72, 52, v46
	v_or_b32_e32 v74, 56, v46
	v_or_b32_e32 v76, 60, v46
	s_ashr_i32 s1, s0, 31
	v_ashrrev_i32_e32 v47, 31, v46
	v_ashrrev_i32_e32 v49, 31, v48
	v_ashrrev_i32_e32 v51, 31, v50
	v_ashrrev_i32_e32 v53, 31, v52
	v_ashrrev_i32_e32 v55, 31, v54
	v_ashrrev_i32_e32 v57, 31, v56
	v_ashrrev_i32_e32 v59, 31, v58
	v_ashrrev_i32_e32 v61, 31, v60
	v_ashrrev_i32_e32 v63, 31, v62
	v_ashrrev_i32_e32 v65, 31, v64
	v_ashrrev_i32_e32 v67, 31, v66
	v_ashrrev_i32_e32 v69, 31, v68
	v_ashrrev_i32_e32 v71, 31, v70
	v_ashrrev_i32_e32 v73, 31, v72
	v_ashrrev_i32_e32 v75, 31, v74
	v_ashrrev_i32_e32 v77, 31, v76
	v_lshl_add_u64 v[78:79], s[0:1], 2, v[2:3]
	v_lshlrev_b64 v[46:47], 12, v[46:47]
	v_lshlrev_b64 v[80:81], 12, v[48:49]
	v_lshlrev_b64 v[50:51], 12, v[50:51]
	v_lshlrev_b64 v[52:53], 12, v[52:53]
	v_lshlrev_b64 v[54:55], 12, v[54:55]
	v_lshlrev_b64 v[56:57], 12, v[56:57]
	v_lshlrev_b64 v[58:59], 12, v[58:59]
	v_lshlrev_b64 v[60:61], 12, v[60:61]
	v_lshlrev_b64 v[62:63], 12, v[62:63]
	v_lshlrev_b64 v[64:65], 12, v[64:65]
	v_lshlrev_b64 v[66:67], 12, v[66:67]
	v_lshlrev_b64 v[68:69], 12, v[68:69]
	v_lshlrev_b64 v[70:71], 12, v[70:71]
	v_lshlrev_b64 v[72:73], 12, v[72:73]
	v_lshlrev_b64 v[74:75], 12, v[74:75]
	v_lshlrev_b64 v[76:77], 12, v[76:77]
	v_lshl_add_u64 v[46:47], v[78:79], 0, v[46:47]
	v_lshl_add_u64 v[80:81], v[78:79], 0, v[80:81]
	v_lshl_add_u64 v[82:83], v[78:79], 0, v[50:51]
	v_lshl_add_u64 v[84:85], v[78:79], 0, v[52:53]
	v_lshl_add_u64 v[86:87], v[78:79], 0, v[54:55]
	v_lshl_add_u64 v[88:89], v[78:79], 0, v[56:57]
	v_lshl_add_u64 v[90:91], v[78:79], 0, v[58:59]
	v_lshl_add_u64 v[92:93], v[78:79], 0, v[60:61]
	v_lshl_add_u64 v[94:95], v[78:79], 0, v[62:63]
	v_lshl_add_u64 v[96:97], v[78:79], 0, v[64:65]
	v_lshl_add_u64 v[98:99], v[78:79], 0, v[66:67]
	v_lshl_add_u64 v[100:101], v[78:79], 0, v[68:69]
	v_lshl_add_u64 v[102:103], v[78:79], 0, v[70:71]
	v_lshl_add_u64 v[104:105], v[78:79], 0, v[72:73]
	v_lshl_add_u64 v[106:107], v[78:79], 0, v[74:75]
	v_lshl_add_u64 v[108:109], v[78:79], 0, v[76:77]
	global_load_dwordx4 v[46:49], v[46:47], off
	s_nop 0
	global_load_dwordx4 v[50:53], v[80:81], off
	global_load_dwordx4 v[54:57], v[82:83], off
	global_load_dwordx4 v[58:61], v[84:85], off
	global_load_dwordx4 v[62:65], v[86:87], off
	global_load_dwordx4 v[66:69], v[88:89], off
	global_load_dwordx4 v[70:73], v[90:91], off
	global_load_dwordx4 v[74:77], v[92:93], off
	global_load_dwordx4 v[78:81], v[94:95], off
	global_load_dwordx4 v[82:85], v[96:97], off
	s_nop 0
	global_load_dwordx4 v[86:89], v[98:99], off
	global_load_dwordx4 v[90:93], v[100:101], off
	global_load_dwordx4 v[94:97], v[102:103], off
	s_nop 0
	global_load_dwordx4 v[98:101], v[104:105], off
	s_nop 0
	global_load_dwordx4 v[102:105], v[106:107], off
	s_nop 0
	global_load_dwordx4 v[106:109], v[108:109], off
	v_add_u32_e32 v6, s0, v9
	s_ashr_i32 s3, s2, 31
	v_ashrrev_i32_e32 v7, 31, v6
	v_lshl_add_u64 v[4:5], s[2:3], 1, v[0:1]
	v_lshlrev_b64 v[122:123], 13, v[6:7]
	v_add_u32_e32 v110, 8, v6
	v_lshl_add_u64 v[122:123], v[4:5], 0, v[122:123]
	v_ashrrev_i32_e32 v111, 31, v110
	v_lshlrev_b64 v[110:111], 13, v[110:111]
	v_add_u32_e32 v112, 16, v6
	v_lshl_add_u64 v[110:111], v[4:5], 0, v[110:111]
	v_ashrrev_i32_e32 v113, 31, v112
	v_lshlrev_b64 v[112:113], 13, v[112:113]
	v_add_u32_e32 v114, 24, v6
	v_lshl_add_u64 v[112:113], v[4:5], 0, v[112:113]
	s_waitcnt vmcnt(15)
	ds_write2_b32 v11, v46, v47 offset1:1
	ds_write2_b32 v11, v48, v49 offset0:2 offset1:3
	s_waitcnt vmcnt(14)
	ds_write2_b32 v12, v50, v51 offset1:1
	ds_write2_b32 v13, v52, v53 offset1:1
	s_waitcnt vmcnt(13)
	ds_write2_b32 v14, v54, v55 offset1:1
	ds_write2_b32 v15, v56, v57 offset1:1
	s_waitcnt vmcnt(12)
	ds_write2_b32 v16, v58, v59 offset1:1
	ds_write2_b32 v17, v60, v61 offset1:1
	s_waitcnt vmcnt(11)
	ds_write2_b32 v18, v62, v63 offset1:1
	ds_write2_b32 v19, v64, v65 offset1:1
	s_waitcnt vmcnt(10)
	ds_write2_b32 v20, v66, v67 offset1:1
	ds_write2_b32 v21, v68, v69 offset1:1
	s_waitcnt vmcnt(9)
	ds_write2_b32 v22, v70, v71 offset1:1
	ds_write2_b32 v23, v72, v73 offset1:1
	s_waitcnt vmcnt(8)
	ds_write2_b32 v24, v74, v75 offset1:1
	ds_write2_b32 v25, v76, v77 offset1:1
	s_waitcnt vmcnt(7)
	ds_write2_b32 v26, v78, v79 offset1:1
	ds_write2_b32 v27, v80, v81 offset1:1
	s_waitcnt vmcnt(6)
	ds_write2_b32 v28, v82, v83 offset1:1
	ds_write2_b32 v29, v84, v85 offset1:1
	s_waitcnt vmcnt(5)
	ds_write2_b32 v30, v86, v87 offset1:1
	ds_write2_b32 v31, v88, v89 offset1:1
	s_waitcnt vmcnt(4)
	ds_write2_b32 v32, v90, v91 offset1:1
	ds_write2_b32 v33, v92, v93 offset1:1
	s_waitcnt vmcnt(3)
	ds_write2_b32 v34, v94, v95 offset1:1
	ds_write2_b32 v35, v96, v97 offset1:1
	s_waitcnt vmcnt(2)
	ds_write2_b32 v36, v98, v99 offset1:1
	ds_write2_b32 v37, v100, v101 offset1:1
	s_waitcnt vmcnt(1)
	ds_write2_b32 v38, v102, v103 offset1:1
	ds_write2_b32 v39, v104, v105 offset1:1
	s_waitcnt vmcnt(0)
; #define LAS __attribute__((address_space(3)))
; __device__ __forceinline__ unsigned pk2(float lo, float hi) { return pg8::cvt_pk_bf16(lo, hi); }
; template <bool GATEMAP = false>
; __device__ __forceinline__ void p0_transpose_item(const float* W, int N, bf16* WT, int ldwt, int koff, const float* gain, LAS float* scr, int item, int lane) {
;     ...
;     const int c = lane & 7;
; #pragma unroll
;     for (int j = 0; j < 8; ++j) { const int n = (lane >> 3) + 8 * j; const LAS float* q = scr + (8 * c) * 65 + n;
;         v4u o; o.x = pk2(q[0 * 65], q[1 * 65]); o.y = pk2(q[2 * 65], q[3 * 65]); o.z = pk2(q[4 * 65], q[5 * 65]); o.w = pk2(q[6 * 65], q[7 * 65]);
;         *(v4u*)(WT + (size_t)(nd0 + n) * ldwt + koff + k0 + 8 * c) = o; }
;     asm volatile("s_waitcnt lgkmcnt(0)" ::: "memory");
; template <int PART>
; __device__ __forceinline__ void phase_prologue_late(const Params& p, LAS unsigned char* lds, int cu0) {
;     ...
;     for (int it = gw; it < I_W2; it += NGW) p0_transpose_item(p.in[23], D, (bf16*)(ws + WS_W2_0), FF, 0, nullptr, scr, it, lane);
;     {
;         const float* Wp = p.in[15]; const float* sc = p.in[16]; const float* Wo = p.in[21]; bf16* WT = (bf16*)(ws + WS_WOUT1);
;         for (int it = gw; it < 1024; it += NGW) {
	ds_write2_b32 v42, v106, v107 offset1:1
	ds_write2_b32 v43, v108, v109 offset1:1
	s_waitcnt lgkmcnt(0)
	ds_read2_b32 v[46:47], v10 offset1:65
	s_waitcnt lgkmcnt(0)
	v_cvt_pk_bf16_f32 v46, v46, v47
	ds_read2_b32 v[48:49], v10 offset0:130 offset1:195
	s_waitcnt lgkmcnt(0)
	v_cvt_pk_bf16_f32 v47, v48, v49
	ds_read2_b32 v[48:49], v44 offset0:4 offset1:69
	s_waitcnt lgkmcnt(0)
	v_cvt_pk_bf16_f32 v48, v48, v49
	ds_read2_b32 v[50:51], v44 offset0:134 offset1:199
	s_waitcnt lgkmcnt(0)
	v_cvt_pk_bf16_f32 v49, v50, v51
	ds_read2_b32 v[50:51], v10 offset0:8 offset1:73
	global_store_dwordx4 v[122:123], v[46:49], off sc1
	v_ashrrev_i32_e32 v115, 31, v114
	v_lshlrev_b64 v[114:115], 13, v[114:115]
	s_waitcnt lgkmcnt(0)
	v_cvt_pk_bf16_f32 v46, v50, v51
	ds_read2_b32 v[48:49], v10 offset0:138 offset1:203
	s_waitcnt lgkmcnt(0)
	v_cvt_pk_bf16_f32 v47, v48, v49
	ds_read2_b32 v[48:49], v44 offset0:12 offset1:77
	s_waitcnt lgkmcnt(0)
	v_cvt_pk_bf16_f32 v48, v48, v49
	ds_read2_b32 v[50:51], v44 offset0:142 offset1:207
	s_waitcnt lgkmcnt(0)
	v_cvt_pk_bf16_f32 v49, v50, v51
	ds_read2_b32 v[50:51], v10 offset0:16 offset1:81
	global_store_dwordx4 v[110:111], v[46:49], off sc1
	v_add_u32_e32 v116, 32, v6
	v_lshl_add_u64 v[114:115], v[4:5], 0, v[114:115]
	s_waitcnt lgkmcnt(0)
	v_cvt_pk_bf16_f32 v46, v50, v51
	ds_read2_b32 v[48:49], v10 offset0:146 offset1:211
	s_waitcnt lgkmcnt(0)
	v_cvt_pk_bf16_f32 v47, v48, v49
	ds_read2_b32 v[48:49], v44 offset0:20 offset1:85
	s_waitcnt lgkmcnt(0)
	v_cvt_pk_bf16_f32 v48, v48, v49
	ds_read2_b32 v[50:51], v44 offset0:150 offset1:215
	s_waitcnt lgkmcnt(0)
	v_cvt_pk_bf16_f32 v49, v50, v51
	ds_read2_b32 v[50:51], v10 offset0:24 offset1:89
	global_store_dwordx4 v[112:113], v[46:49], off sc1
	v_ashrrev_i32_e32 v117, 31, v116
	v_lshlrev_b64 v[116:117], 13, v[116:117]
	s_waitcnt lgkmcnt(0)
	v_cvt_pk_bf16_f32 v46, v50, v51
	ds_read2_b32 v[48:49], v10 offset0:154 offset1:219
	s_waitcnt lgkmcnt(0)
	v_cvt_pk_bf16_f32 v47, v48, v49
	ds_read2_b32 v[48:49], v44 offset0:28 offset1:93
	s_waitcnt lgkmcnt(0)
	v_cvt_pk_bf16_f32 v48, v48, v49
	ds_read2_b32 v[50:51], v44 offset0:158 offset1:223
	s_waitcnt lgkmcnt(0)
	v_cvt_pk_bf16_f32 v49, v50, v51
	ds_read2_b32 v[50:51], v10 offset0:32 offset1:97
	global_store_dwordx4 v[114:115], v[46:49], off sc1
	v_add_u32_e32 v118, 40, v6
	v_lshl_add_u64 v[116:117], v[4:5], 0, v[116:117]
	s_waitcnt lgkmcnt(0)
	v_cvt_pk_bf16_f32 v46, v50, v51
	ds_read2_b32 v[48:49], v10 offset0:162 offset1:227
	s_waitcnt lgkmcnt(0)
	v_cvt_pk_bf16_f32 v47, v48, v49
	ds_read2_b32 v[48:49], v44 offset0:36 offset1:101
	s_waitcnt lgkmcnt(0)
	v_cvt_pk_bf16_f32 v48, v48, v49
	ds_read2_b32 v[50:51], v44 offset0:166 offset1:231
	s_waitcnt lgkmcnt(0)
	v_cvt_pk_bf16_f32 v49, v50, v51
	v_ashrrev_i32_e32 v119, 31, v118
	ds_read2_b32 v[50:51], v10 offset0:40 offset1:105
	global_store_dwordx4 v[116:117], v[46:49], off sc1
	v_lshlrev_b64 v[118:119], 13, v[118:119]
	v_add_u32_e32 v120, 48, v6
	s_waitcnt lgkmcnt(0)
	v_cvt_pk_bf16_f32 v46, v50, v51
	ds_read2_b32 v[48:49], v10 offset0:170 offset1:235
	s_waitcnt lgkmcnt(0)
	v_cvt_pk_bf16_f32 v47, v48, v49
	ds_read2_b32 v[48:49], v44 offset0:44 offset1:109
	v_lshl_add_u64 v[118:119], v[4:5], 0, v[118:119]
	s_waitcnt lgkmcnt(0)
	v_cvt_pk_bf16_f32 v48, v48, v49
	ds_read2_b32 v[50:51], v44 offset0:174 offset1:239
	s_waitcnt lgkmcnt(0)
	v_cvt_pk_bf16_f32 v49, v50, v51
	v_ashrrev_i32_e32 v121, 31, v120
	ds_read2_b32 v[50:51], v10 offset0:48 offset1:113
	global_store_dwordx4 v[118:119], v[46:49], off sc1
	v_lshlrev_b64 v[120:121], 13, v[120:121]
	v_add_u32_e32 v6, 56, v6
	s_waitcnt lgkmcnt(0)
	v_cvt_pk_bf16_f32 v46, v50, v51
	ds_read2_b32 v[48:49], v10 offset0:178 offset1:243
	s_waitcnt lgkmcnt(0)
	v_cvt_pk_bf16_f32 v47, v48, v49
	ds_read2_b32 v[48:49], v44 offset0:52 offset1:117
	v_lshl_add_u64 v[120:121], v[4:5], 0, v[120:121]
	s_waitcnt lgkmcnt(0)
	v_cvt_pk_bf16_f32 v48, v48, v49
	ds_read2_b32 v[50:51], v44 offset0:182 offset1:247
	s_waitcnt lgkmcnt(0)
	v_cvt_pk_bf16_f32 v49, v50, v51
	v_ashrrev_i32_e32 v7, 31, v6
	ds_read2_b32 v[50:51], v10 offset0:56 offset1:121
	global_store_dwordx4 v[120:121], v[46:49], off sc1
	v_lshlrev_b64 v[6:7], 13, v[6:7]
	v_lshl_add_u64 v[4:5], v[4:5], 0, v[6:7]
	s_waitcnt lgkmcnt(0)
	v_cvt_pk_bf16_f32 v46, v50, v51
	ds_read2_b32 v[48:49], v10 offset0:186 offset1:251
	s_waitcnt lgkmcnt(0)
	v_cvt_pk_bf16_f32 v47, v48, v49
	ds_read2_b32 v[48:49], v44 offset0:60 offset1:125
	s_waitcnt lgkmcnt(0)
	v_cvt_pk_bf16_f32 v48, v48, v49
	ds_read2_b32 v[50:51], v44 offset0:190 offset1:255
	s_waitcnt lgkmcnt(0)
	v_cvt_pk_bf16_f32 v49, v50, v51
	global_store_dwordx4 v[4:5], v[46:49], off sc1
	s_waitcnt lgkmcnt(0)
	s_add_i32 s13, s13, s12
	s_add_i32 s4, s4, s5
	s_cmpk_gt_i32 s13, 0x3ff
	s_cbranch_scc0 .LBB0_508
	s_add_u32 s0, s72, 0x1b00000
	v_readlane_b32 s52, v254, 5
	s_addc_u32 s1, s73, 0
	v_readlane_b32 s62, v254, 15
	v_readlane_b32 s63, v254, 16
	s_add_u32 s13, s62, 0xf000
	s_addc_u32 s14, s63, 0
	s_lshl_b32 s2, s10, 9
	s_lshl_b32 s3, s6, 9
	s_lshl_b32 s15, s9, 6
	s_sub_i32 s16, s2, s3
	v_mov_b32_e32 v25, 0
	s_mov_b64 s[2:3], 0x10000
	s_mov_b32 s5, 0
	v_readlane_b32 s53, v254, 6
	v_readlane_b32 s54, v254, 7
	v_readlane_b32 s55, v254, 8
	v_readlane_b32 s56, v254, 9
	v_readlane_b32 s57, v254, 10
	v_readlane_b32 s58, v254, 11
	v_readlane_b32 s59, v254, 12
	v_readlane_b32 s60, v254, 13
	v_readlane_b32 s61, v254, 14
	v_readlane_b32 s64, v254, 17
	v_readlane_b32 s65, v254, 18
	v_readlane_b32 s66, v254, 19
	v_readlane_b32 s67, v254, 20

; template <int PART>
; __device__ __forceinline__ void phase_prologue_late(const Params& p, LAS unsigned char* lds, int cu0) {
;     ...
;             const int g = it >> 8, cb = (it >> 4) & 15, nb2 = it & 15, n = nb2 * 64 + lane;
;             float acc[8];
; #pragma unroll
;             for (int i = 0; i < 8; ++i) acc[i] = 0.f;
;             const float* wp = Wp + ((size_t)g * 128 + cb * 8) * 128;
;             for (int d0 = 0; d0 < 128; d0 += 16) {
;                 float wv[16];
; #pragma unroll
;                 for (int dd = 0; dd < 16; ++dd) wv[dd] = Wo[(size_t)(g * 128 + d0 + dd) * D + n];
; #pragma unroll
;                 for (int dd = 0; dd < 16; ++dd) { const float w = wv[dd] * sc[g * 128 + d0 + dd];
; #pragma unroll
;                     for (int i = 0; i < 8; ++i) acc[i] += wp[i * 128 + d0 + dd] * w; }
.LBB0_511:
	v_add_co_u32_e32 v0, vcc, 0xffff1000, v26
	s_add_u32 s24, s18, s38
	s_nop 0
	v_addc_co_u32_e32 v1, vcc, -1, v27, vcc
	v_add_co_u32_e32 v16, vcc, 0xffff2000, v26
	s_addc_u32 s25, s19, s39
	s_nop 0
	v_addc_co_u32_e32 v17, vcc, -1, v27, vcc
	v_add_co_u32_e32 v18, vcc, 0xffff3000, v26
	s_add_u32 s42, s4, s38
	s_nop 0
	v_addc_co_u32_e32 v19, vcc, -1, v27, vcc
	v_add_co_u32_e32 v38, vcc, 0xffff4000, v26
	s_addc_u32 s43, s17, s39
	s_nop 0
	v_addc_co_u32_e32 v39, vcc, -1, v27, vcc
	v_add_co_u32_e32 v162, vcc, 0xffff5000, v26
	global_load_dword v36, v[26:27], off offset:-4096
	global_load_dword v37, v[26:27], off
	v_addc_co_u32_e32 v163, vcc, -1, v27, vcc
	global_load_dword v24, v[0:1], off
	s_nop 0
	global_load_dwordx4 v[0:3], v25, s[24:25] offset:48
	global_load_dwordx4 v[4:7], v25, s[24:25] offset:32
	global_load_dwordx4 v[12:15], v25, s[24:25]
	global_load_dwordx4 v[8:11], v25, s[24:25] offset:16
	global_load_dword v172, v[16:17], off
	global_load_dword v173, v[18:19], off
	global_load_dwordx4 v[42:45], v25, s[42:43] offset:48
	global_load_dwordx4 v[46:49], v25, s[42:43] offset:32
	global_load_dwordx4 v[50:53], v25, s[42:43] offset:16
	global_load_dwordx4 v[54:57], v25, s[42:43]
	s_nop 0
	global_load_dwordx4 v[16:19], v25, s[42:43] offset:560
	global_load_dwordx4 v[58:61], v25, s[42:43] offset:544
	global_load_dwordx4 v[62:65], v25, s[42:43] offset:528
	global_load_dwordx4 v[66:69], v25, s[42:43] offset:512
	global_load_dwordx4 v[70:73], v25, s[42:43] offset:1072
	global_load_dwordx4 v[74:77], v25, s[42:43] offset:1056
	global_load_dwordx4 v[78:81], v25, s[42:43] offset:1040
	global_load_dwordx4 v[82:85], v25, s[42:43] offset:1024
	global_load_dwordx4 v[20:23], v25, s[42:43] offset:1584
	global_load_dwordx4 v[86:89], v25, s[42:43] offset:1568
	global_load_dwordx4 v[90:93], v25, s[42:43] offset:1552
	global_load_dwordx4 v[94:97], v25, s[42:43] offset:1536
	global_load_dwordx4 v[98:101], v25, s[42:43] offset:2096
	global_load_dwordx4 v[102:105], v25, s[42:43] offset:2080
	global_load_dwordx4 v[106:109], v25, s[42:43] offset:2064
	global_load_dwordx4 v[110:113], v25, s[42:43] offset:2048
	global_load_dwordx4 v[114:117], v25, s[42:43] offset:2608
	global_load_dwordx4 v[118:121], v25, s[42:43] offset:2592
	global_load_dwordx4 v[122:125], v25, s[42:43] offset:2576
	global_load_dwordx4 v[126:129], v25, s[42:43] offset:2560
	global_load_dwordx4 v[130:133], v25, s[42:43] offset:3120
	global_load_dwordx4 v[134:137], v25, s[42:43] offset:3104
	global_load_dwordx4 v[138:141], v25, s[42:43] offset:3088
	global_load_dwordx4 v[142:145], v25, s[42:43] offset:3072
	global_load_dwordx4 v[146:149], v25, s[42:43] offset:3632
	global_load_dwordx4 v[150:153], v25, s[42:43] offset:3616
	global_load_dwordx4 v[154:157], v25, s[42:43] offset:3600
	global_load_dwordx4 v[158:161], v25, s[42:43] offset:3584
	global_load_dword v176, v[38:39], off
	v_add_co_u32_e32 v38, vcc, 0xffff6000, v26
	s_add_i32 s20, s20, 16
	s_nop 0
	v_addc_co_u32_e32 v39, vcc, -1, v27, vcc
	v_add_co_u32_e32 v164, vcc, 0xffff7000, v26
	global_load_dword v162, v[162:163], off
	s_nop 0
	global_load_dword v163, v[38:39], off
	v_addc_co_u32_e32 v165, vcc, -1, v27, vcc
	v_add_co_u32_e32 v38, vcc, 0xffff8000, v26
	s_add_u32 s38, s38, 64
	s_nop 0
	v_addc_co_u32_e32 v39, vcc, -1, v27, vcc
	v_add_co_u32_e32 v166, vcc, 0xffff9000, v26
	global_load_dword v164, v[164:165], off
	s_nop 0
	global_load_dword v165, v[38:39], off
	v_addc_co_u32_e32 v167, vcc, -1, v27, vcc
	v_add_co_u32_e32 v38, vcc, 0xffffa000, v26
	s_addc_u32 s39, s39, 0
	s_nop 0
	v_addc_co_u32_e32 v39, vcc, -1, v27, vcc
	v_add_co_u32_e32 v168, vcc, 0xffffb000, v26
	global_load_dword v166, v[166:167], off
	s_nop 0
	global_load_dword v167, v[38:39], off
	v_addc_co_u32_e32 v169, vcc, -1, v27, vcc
	v_add_co_u32_e32 v38, vcc, 0xffffc000, v26
	s_cmpk_lt_u32 s20, 0x70
	s_nop 0
	v_addc_co_u32_e32 v39, vcc, -1, v27, vcc
	v_add_co_u32_e32 v170, vcc, 0xffffd000, v26
	global_load_dword v168, v[168:169], off
	s_nop 0
	global_load_dword v169, v[38:39], off
	v_addc_co_u32_e32 v171, vcc, -1, v27, vcc
	v_add_co_u32_e32 v38, vcc, 0xffffe000, v26
	s_waitcnt vmcnt(46)
	v_pk_mul_f32 v[2:3], v[36:37], v[2:3]
	v_addc_co_u32_e32 v39, vcc, -1, v27, vcc
	global_load_dword v170, v[170:171], off
	s_nop 0
	global_load_dword v171, v[38:39], off
	s_waitcnt vmcnt(46)
	v_mul_f32_e32 v12, v24, v12
	s_waitcnt vmcnt(44)
	v_mul_f32_e32 v24, v172, v13
	s_waitcnt vmcnt(43)
	v_mul_f32_e32 v14, v173, v14
	s_waitcnt vmcnt(39)
	v_mov_b32_e32 v36, v54
	s_waitcnt vmcnt(35)
	v_mov_b32_e32 v37, v66
	v_mov_b32_e32 v38, v56
	v_mov_b32_e32 v39, v68
	v_mov_b32_e32 v68, v57
	s_waitcnt vmcnt(31)
	v_mov_b32_e32 v56, v82
	s_waitcnt vmcnt(27)
	v_mov_b32_e32 v57, v94
	s_waitcnt vmcnt(23)
	v_mov_b32_e32 v172, v110
	s_waitcnt vmcnt(19)
	v_mov_b32_e32 v173, v126
	v_mov_b32_e32 v66, v55
	v_mov_b32_e32 v94, v83
	v_mov_b32_e32 v126, v111
	s_waitcnt vmcnt(15)
	v_mov_b32_e32 v174, v142
	s_waitcnt vmcnt(11)
	v_mov_b32_e32 v175, v158
	v_pk_fma_f32 v[34:35], v[12:13], v[36:37], v[34:35] op_sel_hi:[0,1,1]
	v_pk_fma_f32 v[32:33], v[12:13], v[56:57], v[32:33] op_sel_hi:[0,1,1]
	v_pk_fma_f32 v[30:31], v[12:13], v[172:173], v[30:31] op_sel_hi:[0,1,1]
	v_mov_b32_e32 v82, v84
	v_mov_b32_e32 v83, v96
	v_mov_b32_e32 v110, v112
	v_mov_b32_e32 v111, v128
	v_mov_b32_e32 v158, v143
	v_pk_fma_f32 v[12:13], v[12:13], v[174:175], v[28:29] op_sel_hi:[0,1,1]
	v_pk_fma_f32 v[28:29], v[24:25], v[66:67], v[34:35] op_sel_hi:[0,1,1]
	v_pk_fma_f32 v[32:33], v[24:25], v[94:95], v[32:33] op_sel_hi:[0,1,1]
	v_pk_fma_f32 v[30:31], v[24:25], v[126:127], v[30:31] op_sel_hi:[0,1,1]
	v_mov_b32_e32 v54, v50
	v_mov_b32_e32 v96, v85
	v_mov_b32_e32 v128, v113
	v_mov_b32_e32 v142, v144
	v_mov_b32_e32 v143, v160
	v_mul_f32_e32 v50, v2, v132
	s_waitcnt vmcnt(10)
; __device__ __forceinline__ v4u pack8(const float (&f)[8]) { v4u w; w.x = pk2(f[0], f[1]); w.y = pk2(f[2], f[3]); w.z = pk2(f[4], f[5]); w.w = pk2(f[6], f[7]); return w; }
; template <int PART>
; __device__ __forceinline__ void phase_prologue_late(const Params& p, LAS unsigned char* lds, int cu0) {
;     ...
;             for (int d0 = 0; d0 < 128; d0 += 16) {
;                 float wv[16];
; #pragma unroll
;                 for (int dd = 0; dd < 16; ++dd) wv[dd] = Wo[(size_t)(g * 128 + d0 + dd) * D + n];
; #pragma unroll
;                 for (int dd = 0; dd < 16; ++dd) { const float w = wv[dd] * sc[g * 128 + d0 + dd];
; #pragma unroll
;                     for (int i = 0; i < 8; ++i) acc[i] += wp[i * 128 + d0 + dd] * w; }
;             }
;             *(v4u*)(WT + (size_t)n * D + g * 128 + cb * 8) = pack8(acc);
	v_mul_f32_e32 v132, v176, v15
	v_pk_fma_f32 v[12:13], v[24:25], v[158:159], v[12:13] op_sel_hi:[0,1,1]
	s_waitcnt vmcnt(8)
	v_pk_mul_f32 v[8:9], v[162:163], v[8:9]
	v_pk_fma_f32 v[28:29], v[14:15], v[38:39], v[28:29] op_sel_hi:[0,1,1]
	v_pk_fma_f32 v[32:33], v[14:15], v[82:83], v[32:33] op_sel_hi:[0,1,1]
	v_pk_fma_f32 v[30:31], v[14:15], v[110:111], v[30:31] op_sel_hi:[0,1,1]
	v_mov_b32_e32 v55, v62
	v_mov_b32_e32 v84, v78
	v_mov_b32_e32 v85, v90
	v_mov_b32_e32 v112, v106
	v_mov_b32_e32 v113, v122
	v_mov_b32_e32 v160, v145
	v_pk_fma_f32 v[12:13], v[14:15], v[142:143], v[12:13] op_sel_hi:[0,1,1]
	v_pk_fma_f32 v[14:15], v[132:133], v[68:69], v[28:29] op_sel_hi:[0,1,1]
	v_pk_fma_f32 v[28:29], v[132:133], v[96:97], v[32:33] op_sel_hi:[0,1,1]
	v_pk_fma_f32 v[30:31], v[132:133], v[128:129], v[30:31] op_sel_hi:[0,1,1]
	v_pk_mul_f32 v[34:35], v[8:9], v[154:155]
	v_mov_b32_e32 v62, v51
	v_mov_b32_e32 v90, v79
	v_mov_b32_e32 v122, v107
	v_mul_f32_e32 v32, v8, v138
	v_pk_fma_f32 v[12:13], v[132:133], v[160:161], v[12:13] op_sel_hi:[0,1,1]
	v_pk_fma_f32 v[14:15], v[8:9], v[54:55], v[14:15] op_sel_hi:[0,1,1]
	v_pk_fma_f32 v[28:29], v[8:9], v[84:85], v[28:29] op_sel_hi:[0,1,1]
	v_pk_fma_f32 v[30:31], v[8:9], v[112:113], v[30:31] op_sel_hi:[0,1,1]
	v_mov_b32_e32 v33, v34
	s_waitcnt vmcnt(6)
	v_pk_mul_f32 v[10:11], v[164:165], v[10:11]
	v_mov_b32_e32 v106, v52
	v_mov_b32_e32 v107, v64
	v_mov_b32_e32 v64, v53
	v_mov_b32_e32 v52, v46
	v_mov_b32_e32 v53, v58
	v_mov_b32_e32 v58, v47
	v_mov_b32_e32 v46, v48
	v_mov_b32_e32 v47, v60
	v_mov_b32_e32 v60, v49
	v_mov_b32_e32 v48, v42
	v_mov_b32_e32 v49, v16
	v_mov_b32_e32 v16, v43
	v_mov_b32_e32 v42, v44
	v_mov_b32_e32 v43, v18
	v_mov_b32_e32 v18, v45
	v_mov_b32_e32 v44, v80
	v_mov_b32_e32 v45, v92
	v_mov_b32_e32 v92, v81
	v_mov_b32_e32 v80, v74
	v_mov_b32_e32 v81, v86
	v_mov_b32_e32 v86, v75
	v_mov_b32_e32 v74, v76
	v_mov_b32_e32 v75, v88
	v_mov_b32_e32 v88, v77
	v_mov_b32_e32 v76, v70
	v_mov_b32_e32 v77, v20
	v_mov_b32_e32 v20, v71
	v_mov_b32_e32 v70, v72
	v_mov_b32_e32 v71, v22
	v_mov_b32_e32 v22, v73
	v_mov_b32_e32 v72, v108
	v_mov_b32_e32 v73, v124
	v_mul_f32_e32 v34, v9, v139
	v_pk_add_f32 v[12:13], v[12:13], v[32:33]
	v_pk_mul_f32 v[36:37], v[10:11], v[156:157]
	v_pk_fma_f32 v[14:15], v[8:9], v[62:63], v[14:15] op_sel:[1,0,0]
	v_pk_fma_f32 v[28:29], v[8:9], v[90:91], v[28:29] op_sel:[1,0,0]
	v_pk_fma_f32 v[8:9], v[8:9], v[122:123], v[30:31] op_sel:[1,0,0]
	v_mov_b32_e32 v124, v109
	v_mul_f32_e32 v32, v10, v140
	s_waitcnt vmcnt(4)
	v_pk_mul_f32 v[4:5], v[166:167], v[4:5]
	v_pk_fma_f32 v[14:15], v[10:11], v[106:107], v[14:15] op_sel_hi:[0,1,1]
	v_pk_fma_f32 v[28:29], v[10:11], v[44:45], v[28:29] op_sel_hi:[0,1,1]
	v_pk_fma_f32 v[8:9], v[10:11], v[72:73], v[8:9] op_sel_hi:[0,1,1]
	v_pk_add_f32 v[12:13], v[12:13], v[34:35]
	v_mov_b32_e32 v33, v36
	v_mov_b32_e32 v108, v102
	v_mov_b32_e32 v109, v118
	v_mul_f32_e32 v38, v11, v141
	v_mov_b32_e32 v39, v37
	v_pk_mul_f32 v[34:35], v[4:5], v[150:151]
	v_pk_fma_f32 v[14:15], v[10:11], v[64:65], v[14:15] op_sel:[1,0,0]
	v_pk_fma_f32 v[28:29], v[10:11], v[92:93], v[28:29] op_sel:[1,0,0]
	v_pk_fma_f32 v[8:9], v[10:11], v[124:125], v[8:9] op_sel:[1,0,0]
	v_pk_add_f32 v[10:11], v[12:13], v[32:33]
	v_mov_b32_e32 v118, v103
	v_mul_f32_e32 v30, v4, v134
	s_waitcnt vmcnt(2)
	v_pk_mul_f32 v[6:7], v[168:169], v[6:7]
	v_pk_fma_f32 v[12:13], v[4:5], v[52:53], v[14:15] op_sel_hi:[0,1,1]
	v_pk_fma_f32 v[14:15], v[4:5], v[80:81], v[28:29] op_sel_hi:[0,1,1]
	v_pk_fma_f32 v[8:9], v[4:5], v[108:109], v[8:9] op_sel_hi:[0,1,1]
	v_pk_add_f32 v[10:11], v[10:11], v[38:39]
	v_mov_b32_e32 v31, v34
	v_mov_b32_e32 v102, v104
	v_mov_b32_e32 v103, v120
	v_mul_f32_e32 v36, v5, v135
	v_mov_b32_e32 v37, v35
	v_pk_mul_f32 v[32:33], v[6:7], v[152:153]
	v_pk_fma_f32 v[12:13], v[4:5], v[58:59], v[12:13] op_sel:[1,0,0]
	v_pk_fma_f32 v[14:15], v[4:5], v[86:87], v[14:15] op_sel:[1,0,0]
	v_pk_fma_f32 v[4:5], v[4:5], v[118:119], v[8:9] op_sel:[1,0,0]
	v_pk_add_f32 v[8:9], v[10:11], v[30:31]
	v_mov_b32_e32 v120, v105
	v_mul_f32_e32 v28, v6, v136
	s_waitcnt vmcnt(0)
	v_pk_mul_f32 v[0:1], v[170:171], v[0:1]
	v_pk_fma_f32 v[10:11], v[6:7], v[46:47], v[12:13] op_sel_hi:[0,1,1]
	v_pk_fma_f32 v[12:13], v[6:7], v[74:75], v[14:15] op_sel_hi:[0,1,1]
	v_pk_fma_f32 v[4:5], v[6:7], v[102:103], v[4:5] op_sel_hi:[0,1,1]
	v_pk_add_f32 v[8:9], v[8:9], v[36:37]
	v_mov_b32_e32 v29, v32
	v_mov_b32_e32 v104, v98
	v_mov_b32_e32 v105, v114
	v_mul_f32_e32 v34, v7, v137
	v_mov_b32_e32 v35, v33
	v_pk_mul_f32 v[30:31], v[0:1], v[146:147]
	v_pk_fma_f32 v[10:11], v[6:7], v[60:61], v[10:11] op_sel:[1,0,0]
	v_pk_fma_f32 v[12:13], v[6:7], v[88:89], v[12:13] op_sel:[1,0,0]
	v_pk_fma_f32 v[4:5], v[6:7], v[120:121], v[4:5] op_sel:[1,0,0]
	v_pk_add_f32 v[6:7], v[8:9], v[28:29]
	v_mov_b32_e32 v114, v99
	v_mul_f32_e32 v14, v0, v130
	v_pk_fma_f32 v[8:9], v[0:1], v[48:49], v[10:11] op_sel_hi:[0,1,1]
	v_pk_fma_f32 v[10:11], v[0:1], v[76:77], v[12:13] op_sel_hi:[0,1,1]
	v_pk_fma_f32 v[4:5], v[0:1], v[104:105], v[4:5] op_sel_hi:[0,1,1]
	v_pk_add_f32 v[6:7], v[6:7], v[34:35]
	v_mov_b32_e32 v15, v30
	v_pk_mul_f32 v[78:79], v[2:3], v[148:149]
	v_mov_b32_e32 v98, v100
	v_mov_b32_e32 v99, v116
	v_mul_f32_e32 v32, v1, v131
	v_mov_b32_e32 v33, v31
	v_pk_fma_f32 v[8:9], v[0:1], v[16:17], v[8:9] op_sel:[1,0,0]
	v_pk_fma_f32 v[10:11], v[0:1], v[20:21], v[10:11] op_sel:[1,0,0]
	v_pk_fma_f32 v[0:1], v[0:1], v[114:115], v[4:5] op_sel:[1,0,0]
	v_pk_add_f32 v[4:5], v[6:7], v[14:15]
	v_mov_b32_e32 v116, v101
	v_mov_b32_e32 v51, v78
	v_pk_fma_f32 v[0:1], v[2:3], v[98:99], v[0:1] op_sel_hi:[0,1,1]
	v_pk_add_f32 v[4:5], v[4:5], v[32:33]
	v_mul_f32_e32 v100, v3, v133
	v_mov_b32_e32 v101, v79
	v_pk_fma_f32 v[6:7], v[2:3], v[42:43], v[8:9] op_sel_hi:[0,1,1]
	v_pk_fma_f32 v[8:9], v[2:3], v[70:71], v[10:11] op_sel_hi:[0,1,1]
	v_pk_fma_f32 v[30:31], v[2:3], v[116:117], v[0:1] op_sel:[1,0,0]
	v_pk_add_f32 v[0:1], v[4:5], v[50:51]
	v_lshl_add_u64 v[26:27], v[26:27], 0, s[2:3]
	v_pk_fma_f32 v[34:35], v[2:3], v[18:19], v[6:7] op_sel:[1,0,0]
	v_pk_fma_f32 v[32:33], v[2:3], v[22:23], v[8:9] op_sel:[1,0,0]
	v_pk_add_f32 v[28:29], v[0:1], v[100:101]
	s_cbranch_scc1 .LBB0_511
	s_lshl_b32 s4, s9, 6
	s_and_b32 s4, s4, 0x3c0
	v_or_b32_e32 v4, s4, v41
	v_lshlrev_b32_e32 v24, 11, v4
	v_lshl_add_u64 v[4:5], s[0:1], 0, v[24:25]
	v_lshl_add_u64 v[4:5], s[22:23], 1, v[4:5]
	s_and_b32 s4, s9, 0xf0
	s_add_i32 s9, s9, s12
	s_add_i32 s15, s15, s16
	v_lshl_add_u64 v[4:5], v[4:5], 0, s[4:5]
	s_cmpk_gt_i32 s9, 0x3ff
	v_cvt_pk_bf16_f32 v0, v34, v35
	v_cvt_pk_bf16_f32 v1, v32, v33
	v_cvt_pk_bf16_f32 v2, v30, v31
	v_cvt_pk_bf16_f32 v3, v28, v29
	global_store_dwordx4 v[4:5], v[0:3], off sc1
	s_cbranch_scc0 .LBB0_510

; __device__ __forceinline__ unsigned pk2(float lo, float hi) { return pg8::cvt_pk_bf16(lo, hi); }
; template <int PART>
; __device__ __forceinline__ void phase_prologue_late(const Params& p, LAS unsigned char* lds, int cu0) {
;     ...
;         for (int i = (blockIdx.x - cu0) * 512 + tid; i < 4 * 128 * 128 / 2; i += nb * 512) {
;             const int e = 2 * i, t = (e >> 7) & 127, s2 = e & 127;
;             const float a = (s2 <= t) ? Wsg[e] : 0.f, b = (s2 + 1 <= t) ? Wsg[e + 1] : 0.f;
;             ((unsigned*)o)[i] = pk2(a, b);
;         }
.LBB0_515:
	s_or_b64 exec, exec, s[12:13]
	v_add_u32_e32 v0, s2, v0
	v_cmp_lt_i32_e32 vcc, s8, v0
	s_waitcnt vmcnt(0)
	v_cvt_pk_bf16_f32 v1, v6, v1
	global_store_dword v[2:3], v1, off sc1
	v_lshl_add_u64 v[2:3], v[2:3], 0, s[4:5]
	s_or_b64 s[6:7], vcc, s[6:7]
	v_add_u32_e32 v4, s3, v4
	s_andn2_b64 exec, exec, s[6:7]
	s_cbranch_execz .LBB0_520

; __device__ __forceinline__ unsigned cvt_pk_bf16(float lo, float hi) { unsigned r; asm volatile("v_cvt_pk_bf16_f32 %0, %1, %2" : "=v"(r) : "v"(lo), "v"(hi)); return r; }
;     __device__ __forceinline__ void operator()(const f32x4 (&acc)[2][2][4][2], const Unit& u, int wr, int wc, int fr, int fq) const {
;     ...
;             for (int m = 0; m < 4; ++m) rsv[ai][m] = ss[row0 + ai * HALF + m * 16];
; #pragma unroll
;         for (int ai = 0; ai < 2; ++ai)
; #pragma unroll
;             for (int m = 0; m < 4; ++m) rsv[ai][m] = __builtin_amdgcn_rsqf(rsv[ai][m] * (1.0f / 1024.0f) + RMS_EPS);
; #pragma unroll
;         for (int ai = 0; ai < 2; ++ai)
; #pragma unroll
;             for (int m = 0; m < 4; ++m) {
;                 if (ai == 1 && !whole) continue;
;                 const int row = row0 + ai * HALF + m * 16;
;                 const float rs = rsv[ai][m];
;                 float s1 = 0.f, s2 = 0.f;
;                 bf16_t* rowp = BLK ? O + ((size_t)u.pm * (ldc >> 6) + (size_t)(col0 >> 6)) * 16384 + (size_t)((col0 >> 5) & 1) * 8192 + (size_t)(row - u.pm * BM) * 32 + (col0 & 31) : O + (size_t)row * ldc + col0;
; #pragma unroll
;                 for (int bj = 0; bj < 2; ++bj) {
;                     if (bj == 1 && !whole) continue;
;                     f32x4 v0 = acc[ai][bj][m][0] * rs, v1 = acc[ai][bj][m][1] * rs;
;                     if (ACT == 1) {
; #pragma unroll
;                         for (int j = 0; j < 4; ++j) { const float a = fmaxf(v0[j], 0.f), b = fmaxf(v1[j], 0.f); v0[j] = a * a; v1[j] = b * b; }
;                     }
;                     u32x4 w; w.x = cvt_pk_bf16(v0[0], v0[1]); w.y = cvt_pk_bf16(v0[2], v0[3]); w.z = cvt_pk_bf16(v1[0], v1[1]); w.w = cvt_pk_bf16(v1[2], v1[3]);
;                     *(u32x4*)(rowp + (BLK ? bj * 2 * 16384 : bj * HALF)) = w;
.LBB0_1221:
	s_lshl_b32 s6, s46, 8
	s_cmp_gt_i32 s86, 0
	s_cselect_b32 s7, 0x80, 0
	s_or_b32 s18, s7, s6
	v_add_u32_e32 v128, s18, v210
	v_ashrrev_i32_e32 v129, 31, v128
	v_lshl_add_u64 v[130:131], v[128:129], 2, s[4:5]
	global_load_dword v156, v[130:131], off
	v_or_b32_e32 v140, 16, v128
	v_or_b32_e32 v138, 32, v128
	v_or_b32_e32 v136, 48, v128
	v_add_u32_e32 v134, 0x80, v128
	v_add_u32_e32 v132, 0x90, v128
	v_add_u32_e32 v130, 0xa0, v128
	v_add_u32_e32 v128, 0xb0, v128
	v_ashrrev_i32_e32 v141, 31, v140
	v_ashrrev_i32_e32 v139, 31, v138
	v_ashrrev_i32_e32 v137, 31, v136
	v_ashrrev_i32_e32 v135, 31, v134
	v_ashrrev_i32_e32 v133, 31, v132
	v_ashrrev_i32_e32 v131, 31, v130
	v_ashrrev_i32_e32 v129, 31, v128
	v_lshl_add_u64 v[142:143], v[140:141], 2, s[4:5]
	v_lshl_add_u64 v[144:145], v[138:139], 2, s[4:5]
	v_lshl_add_u64 v[146:147], v[136:137], 2, s[4:5]
	v_lshl_add_u64 v[148:149], v[134:135], 2, s[4:5]
	v_lshl_add_u64 v[150:151], v[132:133], 2, s[4:5]
	v_lshl_add_u64 v[152:153], v[130:131], 2, s[4:5]
	v_lshl_add_u64 v[154:155], v[128:129], 2, s[4:5]
	global_load_dword v141, v[142:143], off
	global_load_dword v139, v[144:145], off
	global_load_dword v137, v[146:147], off
	global_load_dword v135, v[148:149], off
	global_load_dword v133, v[150:151], off
	global_load_dword v131, v[152:153], off
	global_load_dword v129, v[154:155], off
	s_lshl_b32 s18, s48, 8
	s_or_b32 s18, s18, s66
	s_cmp_gt_i32 s85, 0
	v_add_u32_e32 v142, s7, v210
	s_cselect_b32 s7, 0x80, 0
	s_ashr_i32 s47, s46, 31
	s_or_b32 s7, s7, s18
	s_lshl_b64 s[28:29], s[46:47], 21
	s_ashr_i32 s46, s7, 6
	s_ashr_i32 s47, s46, 31
	s_lshl_b64 s[46:47], s[46:47], 15
	s_add_u32 s7, s34, s28
	s_addc_u32 s18, s35, s29
	s_add_u32 s7, s7, s46
	s_addc_u32 s18, s18, s47
	v_ashrrev_i32_e32 v143, 31, v142
	s_add_u32 s46, s7, s81
	v_lshlrev_b64 v[142:143], 6, v[142:143]
	s_addc_u32 s47, s18, 0
	v_lshl_add_u64 v[142:143], s[46:47], 0, v[142:143]
	v_lshl_add_u64 v[142:143], v[142:143], 0, v[200:201]
	s_and_b64 vcc, exec, s[2:3]
	s_waitcnt vmcnt(0)
	v_fmamk_f32 v144, v156, 0x3a800000, v211
	v_rsq_f32_e32 v144, v144
	s_nop 0
	v_pk_mul_f32 v[126:127], v[126:127], v[144:145] op_sel_hi:[1,0]
	v_pk_mul_f32 v[124:125], v[124:125], v[144:145] op_sel_hi:[1,0]
	v_pk_mul_f32 v[122:123], v[122:123], v[144:145] op_sel_hi:[1,0]
	v_pk_mul_f32 v[120:121], v[120:121], v[144:145] op_sel_hi:[1,0]
	v_max_f32_e32 v125, 0, v125
	v_max_f32_e32 v120, 0, v120
	v_max_f32_e32 v121, 0, v121
	v_max_f32_e32 v126, 0, v126
	v_max_f32_e32 v122, 0, v122
	v_max_f32_e32 v127, 0, v127
	v_max_f32_e32 v123, 0, v123
	v_max_f32_e32 v124, 0, v124
	v_mul_f32_e32 v145, v120, v120
	v_mul_f32_e32 v120, v125, v125
	v_mul_f32_e32 v125, v121, v121
	v_mul_f32_e32 v121, v126, v126
	v_mul_f32_e32 v126, v122, v122
	v_mul_f32_e32 v122, v127, v127
	v_mul_f32_e32 v123, v123, v123
	v_mul_f32_e32 v124, v124, v124
	v_cvt_pk_bf16_f32 v120, v124, v120
	v_cvt_pk_bf16_f32 v121, v121, v122
	v_cvt_pk_bf16_f32 v122, v145, v125
	v_cvt_pk_bf16_f32 v123, v126, v123
	global_store_dwordx4 v[142:143], v[120:123], off sc1
	s_cbranch_vccnz .LBB0_1223
	v_mov_b32_e32 v145, v144
	v_mov_b32_e32 v120, v144
	v_mov_b32_e32 v121, v144
	v_pk_mul_f32 v[92:93], v[92:93], v[144:145]
	v_pk_mul_f32 v[96:97], v[96:97], v[144:145]
	v_pk_mul_f32 v[94:95], v[94:95], v[120:121]
	v_max_f32_e32 v92, 0, v92
	v_pk_mul_f32 v[98:99], v[98:99], v[120:121]
	v_max_f32_e32 v96, 0, v96
	v_mul_f32_e32 v120, v92, v92
	v_max_f32_e32 v92, 0, v97
	v_max_f32_e32 v93, 0, v93
	v_max_f32_e32 v94, 0, v94
	v_mul_f32_e32 v96, v96, v96
	v_mul_f32_e32 v92, v92, v92
	v_mul_f32_e32 v97, v93, v93
	v_max_f32_e32 v93, 0, v98
	v_mul_f32_e32 v98, v94, v94
	v_max_f32_e32 v94, 0, v99
	v_mul_f32_e32 v93, v93, v93
	v_max_f32_e32 v95, 0, v95
	v_mul_f32_e32 v94, v94, v94
	v_cvt_pk_bf16_f32 v92, v96, v92
	v_add_co_u32_e32 v96, vcc, 0x10000, v142
	v_mul_f32_e32 v95, v95, v95
	v_cvt_pk_bf16_f32 v93, v93, v94
	v_cvt_pk_bf16_f32 v94, v120, v97
	s_nop 0
	v_addc_co_u32_e32 v97, vcc, 0, v143, vcc
	v_cvt_pk_bf16_f32 v95, v98, v95
	global_store_dwordx4 v[96:97], v[92:95], off sc1
.LBB0_1223:
	s_nop 1
	v_fmamk_f32 v92, v141, 0x3a800000, v211
	v_rsq_f32_e32 v94, v92
	v_subrev_u32_e32 v92, s6, v140
	v_ashrrev_i32_e32 v93, 31, v92
	v_lshlrev_b64 v[92:93], 6, v[92:93]
	v_pk_mul_f32 v[96:97], v[118:119], v[94:95] op_sel_hi:[1,0]
	v_pk_mul_f32 v[98:99], v[116:117], v[94:95] op_sel_hi:[1,0]
	v_pk_mul_f32 v[112:113], v[112:113], v[94:95] op_sel_hi:[1,0]
	v_lshl_add_u64 v[92:93], s[46:47], 0, v[92:93]
	v_pk_mul_f32 v[114:115], v[114:115], v[94:95] op_sel_hi:[1,0]
	v_max_f32_e32 v95, 0, v98
	v_max_f32_e32 v98, 0, v112
	v_max_f32_e32 v99, 0, v99
	v_max_f32_e32 v96, 0, v96
	v_lshl_add_u64 v[92:93], v[92:93], 0, v[200:201]
	v_mul_f32_e32 v98, v98, v98
	v_max_f32_e32 v112, 0, v113
	v_mul_f32_e32 v99, v99, v99
	v_max_f32_e32 v113, 0, v114
	v_mul_f32_e32 v114, v96, v96
	v_max_f32_e32 v96, 0, v97
	v_max_f32_e32 v97, 0, v115
	s_and_b64 vcc, exec, s[2:3]
	v_mul_f32_e32 v95, v95, v95
	v_mul_f32_e32 v112, v112, v112
	v_mul_f32_e32 v113, v113, v113
	v_mul_f32_e32 v115, v96, v96
	v_mul_f32_e32 v116, v97, v97
	v_cvt_pk_bf16_f32 v96, v95, v99
	v_cvt_pk_bf16_f32 v97, v114, v115
	v_cvt_pk_bf16_f32 v98, v98, v112
	v_cvt_pk_bf16_f32 v99, v113, v116
	global_store_dwordx4 v[92:93], v[96:99], off sc1
	s_cbranch_vccnz .LBB0_1225
	v_mov_b32_e32 v95, v94
	v_mov_b32_e32 v96, v94
	v_mov_b32_e32 v97, v94
	v_pk_mul_f32 v[80:81], v[80:81], v[94:95]
	v_pk_mul_f32 v[84:85], v[84:85], v[94:95]
	v_pk_mul_f32 v[82:83], v[82:83], v[96:97]
	v_max_f32_e32 v80, 0, v80
	v_pk_mul_f32 v[86:87], v[86:87], v[96:97]
	v_max_f32_e32 v84, 0, v84
	v_mul_f32_e32 v94, v80, v80
	v_max_f32_e32 v80, 0, v85
	v_max_f32_e32 v81, 0, v81
	v_max_f32_e32 v82, 0, v82
	v_mul_f32_e32 v84, v84, v84
	v_mul_f32_e32 v80, v80, v80
	v_mul_f32_e32 v85, v81, v81
	v_max_f32_e32 v81, 0, v86
	v_mul_f32_e32 v86, v82, v82
	v_max_f32_e32 v82, 0, v87
	v_mul_f32_e32 v81, v81, v81
	v_max_f32_e32 v83, 0, v83
	v_mul_f32_e32 v82, v82, v82
	v_cvt_pk_bf16_f32 v80, v84, v80
	v_add_co_u32_e32 v84, vcc, 0x10000, v92
	v_mul_f32_e32 v83, v83, v83
	v_cvt_pk_bf16_f32 v81, v81, v82
	v_cvt_pk_bf16_f32 v82, v94, v85
	s_nop 0
	v_addc_co_u32_e32 v85, vcc, 0, v93, vcc
	v_cvt_pk_bf16_f32 v83, v86, v83
	global_store_dwordx4 v[84:85], v[80:83], off sc1
; __device__ __forceinline__ unsigned cvt_pk_bf16(float lo, float hi) { unsigned r; asm volatile("v_cvt_pk_bf16_f32 %0, %1, %2" : "=v"(r) : "v"(lo), "v"(hi)); return r; }
;     __device__ __forceinline__ void operator()(const f32x4 (&acc)[2][2][4][2], const Unit& u, int wr, int wc, int fr, int fq) const {
;     ...
;             for (int m = 0; m < 4; ++m) rsv[ai][m] = __builtin_amdgcn_rsqf(rsv[ai][m] * (1.0f / 1024.0f) + RMS_EPS);
; #pragma unroll
;         for (int ai = 0; ai < 2; ++ai)
; #pragma unroll
;             for (int m = 0; m < 4; ++m) {
;                 if (ai == 1 && !whole) continue;
;                 const int row = row0 + ai * HALF + m * 16;
;                 const float rs = rsv[ai][m];
;                 float s1 = 0.f, s2 = 0.f;
;                 bf16_t* rowp = BLK ? O + ((size_t)u.pm * (ldc >> 6) + (size_t)(col0 >> 6)) * 16384 + (size_t)((col0 >> 5) & 1) * 8192 + (size_t)(row - u.pm * BM) * 32 + (col0 & 31) : O + (size_t)row * ldc + col0;
; #pragma unroll
;                 for (int bj = 0; bj < 2; ++bj) {
;                     if (bj == 1 && !whole) continue;
;                     f32x4 v0 = acc[ai][bj][m][0] * rs, v1 = acc[ai][bj][m][1] * rs;
;                     if (ACT == 1) {
; #pragma unroll
;                         for (int j = 0; j < 4; ++j) { const float a = fmaxf(v0[j], 0.f), b = fmaxf(v1[j], 0.f); v0[j] = a * a; v1[j] = b * b; }
;                     }
;                     u32x4 w; w.x = cvt_pk_bf16(v0[0], v0[1]); w.y = cvt_pk_bf16(v0[2], v0[3]); w.z = cvt_pk_bf16(v1[0], v1[1]); w.w = cvt_pk_bf16(v1[2], v1[3]);
;                     *(u32x4*)(rowp + (BLK ? bj * 2 * 16384 : bj * HALF)) = w;
.LBB0_1225:
	s_nop 1
	v_fmamk_f32 v80, v139, 0x3a800000, v211
	v_rsq_f32_e32 v82, v80
	v_subrev_u32_e32 v80, s6, v138
	v_ashrrev_i32_e32 v81, 31, v80
	v_lshlrev_b64 v[80:81], 6, v[80:81]
	v_pk_mul_f32 v[84:85], v[110:111], v[82:83] op_sel_hi:[1,0]
	v_pk_mul_f32 v[86:87], v[108:109], v[82:83] op_sel_hi:[1,0]
	v_pk_mul_f32 v[94:95], v[104:105], v[82:83] op_sel_hi:[1,0]
	v_lshl_add_u64 v[80:81], s[46:47], 0, v[80:81]
	v_pk_mul_f32 v[92:93], v[106:107], v[82:83] op_sel_hi:[1,0]
	v_max_f32_e32 v83, 0, v86
	v_max_f32_e32 v86, 0, v94
	v_max_f32_e32 v87, 0, v87
	v_max_f32_e32 v84, 0, v84
	v_lshl_add_u64 v[80:81], v[80:81], 0, v[200:201]
	v_mul_f32_e32 v86, v86, v86
	v_max_f32_e32 v94, 0, v95
	v_mul_f32_e32 v87, v87, v87
	v_max_f32_e32 v92, 0, v92
	v_mul_f32_e32 v95, v84, v84
	v_max_f32_e32 v84, 0, v85
	v_max_f32_e32 v85, 0, v93
	s_and_b64 vcc, exec, s[2:3]
	v_mul_f32_e32 v83, v83, v83
	v_mul_f32_e32 v94, v94, v94
	v_mul_f32_e32 v92, v92, v92
	v_mul_f32_e32 v93, v84, v84
	v_mul_f32_e32 v96, v85, v85
	v_cvt_pk_bf16_f32 v84, v83, v87
	v_cvt_pk_bf16_f32 v85, v95, v93
	v_cvt_pk_bf16_f32 v86, v86, v94
	v_cvt_pk_bf16_f32 v87, v92, v96
	global_store_dwordx4 v[80:81], v[84:87], off sc1
	s_cbranch_vccnz .LBB0_1227
	v_mov_b32_e32 v83, v82
	v_mov_b32_e32 v84, v82
	v_mov_b32_e32 v85, v82
	v_pk_mul_f32 v[72:73], v[72:73], v[82:83]
	v_pk_mul_f32 v[76:77], v[76:77], v[82:83]
	v_pk_mul_f32 v[74:75], v[74:75], v[84:85]
	v_max_f32_e32 v72, 0, v72
	v_pk_mul_f32 v[78:79], v[78:79], v[84:85]
	v_max_f32_e32 v76, 0, v76
	v_mul_f32_e32 v82, v72, v72
	v_max_f32_e32 v72, 0, v77
	v_max_f32_e32 v73, 0, v73
	v_max_f32_e32 v74, 0, v74
	v_mul_f32_e32 v76, v76, v76
	v_mul_f32_e32 v72, v72, v72
	v_mul_f32_e32 v77, v73, v73
	v_max_f32_e32 v73, 0, v78
	v_mul_f32_e32 v78, v74, v74
	v_max_f32_e32 v74, 0, v79
	v_mul_f32_e32 v73, v73, v73
	v_max_f32_e32 v75, 0, v75
	v_mul_f32_e32 v74, v74, v74
	v_cvt_pk_bf16_f32 v72, v76, v72
	v_add_co_u32_e32 v76, vcc, 0x10000, v80
	v_mul_f32_e32 v75, v75, v75
	v_cvt_pk_bf16_f32 v73, v73, v74
	v_cvt_pk_bf16_f32 v74, v82, v77
	s_nop 0
	v_addc_co_u32_e32 v77, vcc, 0, v81, vcc
	v_cvt_pk_bf16_f32 v75, v78, v75
	global_store_dwordx4 v[76:77], v[72:75], off sc1
.LBB0_1227:
	s_nop 1
	v_fmamk_f32 v72, v137, 0x3a800000, v211
	v_rsq_f32_e32 v76, v72
	v_subrev_u32_e32 v72, s6, v136
	v_ashrrev_i32_e32 v73, 31, v72
	v_lshlrev_b64 v[72:73], 6, v[72:73]
	v_lshl_add_u64 v[72:73], s[46:47], 0, v[72:73]
	v_pk_mul_f32 v[78:79], v[100:101], v[76:77] op_sel_hi:[1,0]
	v_pk_mul_f32 v[82:83], v[88:89], v[76:77] op_sel_hi:[1,0]
	v_lshl_add_u64 v[74:75], v[72:73], 0, v[200:201]
	v_pk_mul_f32 v[72:73], v[102:103], v[76:77] op_sel_hi:[1,0]
	v_pk_mul_f32 v[80:81], v[90:91], v[76:77] op_sel_hi:[1,0]
	v_max_f32_e32 v77, 0, v78
	v_max_f32_e32 v78, 0, v82
	v_mul_f32_e32 v82, v78, v78
	v_max_f32_e32 v78, 0, v79
	v_max_f32_e32 v79, 0, v83
	v_mul_f32_e32 v83, v79, v79
	v_max_f32_e32 v79, 0, v80
	v_mul_f32_e32 v84, v79, v79
	v_max_f32_e32 v79, 0, v81
	v_mul_f32_e32 v78, v78, v78
	v_max_f32_e32 v72, 0, v72
	v_max_f32_e32 v73, 0, v73
	v_mul_f32_e32 v81, v79, v79
	s_and_b64 vcc, exec, s[2:3]
	v_mul_f32_e32 v77, v77, v77
	v_mul_f32_e32 v72, v72, v72
	v_mul_f32_e32 v73, v73, v73
	v_cvt_pk_bf16_f32 v78, v77, v78
	v_cvt_pk_bf16_f32 v79, v72, v73
	v_cvt_pk_bf16_f32 v80, v82, v83
	v_cvt_pk_bf16_f32 v81, v84, v81
	global_store_dwordx4 v[74:75], v[78:81], off sc1
	s_cbranch_vccz .LBB0_1229
	s_andn2_b64 vcc, exec, s[42:43]
	s_mov_b64 s[2:3], -1
	s_cbranch_vccnz .LBB0_1191
	s_branch .LBB0_1230
.LBB0_1229:
	v_mov_b32_e32 v77, v76
	v_mov_b32_e32 v84, v76
	v_mov_b32_e32 v85, v76
	v_pk_mul_f32 v[64:65], v[64:65], v[76:77]
	v_fmamk_f32 v72, v135, 0x3a800000, v211
	v_pk_mul_f32 v[68:69], v[68:69], v[76:77]
	v_pk_mul_f32 v[66:67], v[66:67], v[84:85]
	v_max_f32_e32 v64, 0, v64
	v_rsq_f32_e32 v78, v72
	v_pk_mul_f32 v[70:71], v[70:71], v[84:85]
	v_max_f32_e32 v68, 0, v68
	v_mul_f32_e32 v73, v64, v64
	v_max_f32_e32 v64, 0, v69
	v_max_f32_e32 v65, 0, v65
	v_max_f32_e32 v66, 0, v66
	v_mul_f32_e32 v68, v68, v68
	v_mul_f32_e32 v64, v64, v64
	v_mul_f32_e32 v69, v65, v65
	v_max_f32_e32 v65, 0, v70
	v_mul_f32_e32 v70, v66, v66
	v_max_f32_e32 v66, 0, v71
	v_mul_f32_e32 v65, v65, v65
	v_max_f32_e32 v67, 0, v67
	v_mul_f32_e32 v66, v66, v66
	v_cvt_pk_bf16_f32 v64, v68, v64
	v_add_co_u32_e32 v68, vcc, s65, v74
	v_mul_f32_e32 v67, v67, v67
	v_cvt_pk_bf16_f32 v65, v65, v66
	v_cvt_pk_bf16_f32 v66, v73, v69
	s_nop 0
	v_addc_co_u32_e32 v69, vcc, 0, v75, vcc
	v_cvt_pk_bf16_f32 v67, v70, v67
	global_store_dwordx4 v[68:69], v[64:67], off sc1
	v_pk_mul_f32 v[56:57], v[56:57], v[78:79] op_sel_hi:[1,0]
	v_pk_mul_f32 v[60:61], v[60:61], v[78:79] op_sel_hi:[1,0]
	v_subrev_u32_e32 v64, s6, v134
	v_ashrrev_i32_e32 v65, 31, v64
	v_pk_mul_f32 v[58:59], v[58:59], v[78:79] op_sel_hi:[1,0]
	v_max_f32_e32 v56, 0, v56
	v_lshlrev_b64 v[64:65], 6, v[64:65]
	v_pk_mul_f32 v[62:63], v[62:63], v[78:79] op_sel_hi:[1,0]
	v_mul_f32_e32 v66, v56, v56
	v_max_f32_e32 v56, 0, v61
	v_max_f32_e32 v57, 0, v57
	v_max_f32_e32 v58, 0, v58
	v_lshl_add_u64 v[64:65], s[46:47], 0, v[64:65]
	v_max_f32_e32 v60, 0, v60
	v_mul_f32_e32 v56, v56, v56
	v_mul_f32_e32 v61, v57, v57
	v_max_f32_e32 v57, 0, v62
	v_mul_f32_e32 v62, v58, v58
	v_max_f32_e32 v58, 0, v63
	v_max_f32_e32 v59, 0, v59
	v_pk_mul_f32 v[48:49], v[48:49], v[78:79] op_sel_hi:[1,0]
	v_fmamk_f32 v72, v133, 0x3a800000, v211
	v_lshl_add_u64 v[64:65], v[64:65], 0, v[200:201]
	v_mul_f32_e32 v60, v60, v60
	v_mul_f32_e32 v57, v57, v57
	v_mul_f32_e32 v58, v58, v58
	v_mul_f32_e32 v59, v59, v59
	v_cvt_pk_bf16_f32 v56, v60, v56
	v_pk_mul_f32 v[52:53], v[52:53], v[78:79] op_sel_hi:[1,0]
	v_pk_mul_f32 v[50:51], v[50:51], v[78:79] op_sel_hi:[1,0]
; __device__ __forceinline__ unsigned cvt_pk_bf16(float lo, float hi) { unsigned r; asm volatile("v_cvt_pk_bf16_f32 %0, %1, %2" : "=v"(r) : "v"(lo), "v"(hi)); return r; }
;     __device__ __forceinline__ void operator()(const f32x4 (&acc)[2][2][4][2], const Unit& u, int wr, int wc, int fr, int fq) const {
;     ...
;             for (int m = 0; m < 4; ++m) rsv[ai][m] = __builtin_amdgcn_rsqf(rsv[ai][m] * (1.0f / 1024.0f) + RMS_EPS);
; #pragma unroll
;         for (int ai = 0; ai < 2; ++ai)
; #pragma unroll
;             for (int m = 0; m < 4; ++m) {
;                 if (ai == 1 && !whole) continue;
;                 const int row = row0 + ai * HALF + m * 16;
;                 const float rs = rsv[ai][m];
;                 float s1 = 0.f, s2 = 0.f;
;                 bf16_t* rowp = BLK ? O + ((size_t)u.pm * (ldc >> 6) + (size_t)(col0 >> 6)) * 16384 + (size_t)((col0 >> 5) & 1) * 8192 + (size_t)(row - u.pm * BM) * 32 + (col0 & 31) : O + (size_t)row * ldc + col0;
; #pragma unroll
;                 for (int bj = 0; bj < 2; ++bj) {
;                     if (bj == 1 && !whole) continue;
;                     f32x4 v0 = acc[ai][bj][m][0] * rs, v1 = acc[ai][bj][m][1] * rs;
;                     if (ACT == 1) {
; #pragma unroll
;                         for (int j = 0; j < 4; ++j) { const float a = fmaxf(v0[j], 0.f), b = fmaxf(v1[j], 0.f); v0[j] = a * a; v1[j] = b * b; }
;                     }
;                     u32x4 w; w.x = cvt_pk_bf16(v0[0], v0[1]); w.y = cvt_pk_bf16(v0[2], v0[3]); w.z = cvt_pk_bf16(v1[0], v1[1]); w.w = cvt_pk_bf16(v1[2], v1[3]);
;                     *(u32x4*)(rowp + (BLK ? bj * 2 * 16384 : bj * HALF)) = w;
	v_max_f32_e32 v48, 0, v48
	v_rsq_f32_e32 v80, v72
	v_cvt_pk_bf16_f32 v57, v57, v58
	v_cvt_pk_bf16_f32 v58, v66, v61
	v_cvt_pk_bf16_f32 v59, v62, v59
	global_store_dwordx4 v[64:65], v[56:59], off sc1
	v_pk_mul_f32 v[54:55], v[54:55], v[78:79] op_sel_hi:[1,0]
	v_max_f32_e32 v52, 0, v52
	v_mul_f32_e32 v56, v48, v48
	v_max_f32_e32 v48, 0, v53
	v_max_f32_e32 v49, 0, v49
	v_max_f32_e32 v50, 0, v50
	v_mul_f32_e32 v52, v52, v52
	v_mul_f32_e32 v48, v48, v48
	v_mul_f32_e32 v53, v49, v49
	v_max_f32_e32 v49, 0, v54
	v_mul_f32_e32 v54, v50, v50
	v_max_f32_e32 v50, 0, v55
	v_mul_f32_e32 v49, v49, v49
	v_max_f32_e32 v51, 0, v51
	v_mul_f32_e32 v50, v50, v50
	v_cvt_pk_bf16_f32 v48, v52, v48
	v_add_co_u32_e32 v52, vcc, s65, v64
	v_mul_f32_e32 v51, v51, v51
	v_cvt_pk_bf16_f32 v49, v49, v50
	v_cvt_pk_bf16_f32 v50, v56, v53
	s_nop 0
	v_addc_co_u32_e32 v53, vcc, 0, v65, vcc
	v_cvt_pk_bf16_f32 v51, v54, v51
	global_store_dwordx4 v[52:53], v[48:51], off sc1
	v_pk_mul_f32 v[40:41], v[40:41], v[80:81] op_sel_hi:[1,0]
	v_pk_mul_f32 v[44:45], v[44:45], v[80:81] op_sel_hi:[1,0]
	v_subrev_u32_e32 v48, s6, v132
	v_ashrrev_i32_e32 v49, 31, v48
	v_pk_mul_f32 v[42:43], v[42:43], v[80:81] op_sel_hi:[1,0]
	v_max_f32_e32 v40, 0, v40
	v_lshlrev_b64 v[48:49], 6, v[48:49]
	v_pk_mul_f32 v[46:47], v[46:47], v[80:81] op_sel_hi:[1,0]
	v_mul_f32_e32 v50, v40, v40
	v_max_f32_e32 v40, 0, v45
	v_max_f32_e32 v41, 0, v41
	v_max_f32_e32 v42, 0, v42
	v_lshl_add_u64 v[48:49], s[46:47], 0, v[48:49]
	v_max_f32_e32 v44, 0, v44
	v_mul_f32_e32 v40, v40, v40
	v_mul_f32_e32 v45, v41, v41
	v_max_f32_e32 v41, 0, v46
	v_mul_f32_e32 v46, v42, v42
	v_max_f32_e32 v42, 0, v47
	v_max_f32_e32 v43, 0, v43
	v_pk_mul_f32 v[32:33], v[32:33], v[80:81] op_sel_hi:[1,0]
	v_fmamk_f32 v72, v131, 0x3a800000, v211
	v_lshl_add_u64 v[48:49], v[48:49], 0, v[200:201]
	v_mul_f32_e32 v44, v44, v44
	v_mul_f32_e32 v41, v41, v41
	v_mul_f32_e32 v42, v42, v42
	v_mul_f32_e32 v43, v43, v43
	v_cvt_pk_bf16_f32 v40, v44, v40
	v_pk_mul_f32 v[36:37], v[36:37], v[80:81] op_sel_hi:[1,0]
	v_pk_mul_f32 v[34:35], v[34:35], v[80:81] op_sel_hi:[1,0]
	v_max_f32_e32 v32, 0, v32
	v_rsq_f32_e32 v82, v72
	v_cvt_pk_bf16_f32 v41, v41, v42
	v_cvt_pk_bf16_f32 v42, v50, v45
	v_cvt_pk_bf16_f32 v43, v46, v43
	global_store_dwordx4 v[48:49], v[40:43], off sc1
	v_pk_mul_f32 v[38:39], v[38:39], v[80:81] op_sel_hi:[1,0]
	v_max_f32_e32 v36, 0, v36
	v_mul_f32_e32 v40, v32, v32
	v_max_f32_e32 v32, 0, v37
	v_max_f32_e32 v33, 0, v33
	v_max_f32_e32 v34, 0, v34
	v_mul_f32_e32 v36, v36, v36
	v_mul_f32_e32 v32, v32, v32
	v_mul_f32_e32 v37, v33, v33
	v_max_f32_e32 v33, 0, v38
	v_mul_f32_e32 v38, v34, v34
	v_max_f32_e32 v34, 0, v39
	v_mul_f32_e32 v33, v33, v33
	v_max_f32_e32 v35, 0, v35
	v_mul_f32_e32 v34, v34, v34
	v_cvt_pk_bf16_f32 v32, v36, v32
	v_add_co_u32_e32 v36, vcc, s65, v48
	v_mul_f32_e32 v35, v35, v35
	v_cvt_pk_bf16_f32 v33, v33, v34
	v_cvt_pk_bf16_f32 v34, v40, v37
	s_nop 0
	v_addc_co_u32_e32 v37, vcc, 0, v49, vcc
	v_cvt_pk_bf16_f32 v35, v38, v35
	global_store_dwordx4 v[36:37], v[32:35], off sc1
	v_pk_mul_f32 v[24:25], v[24:25], v[82:83] op_sel_hi:[1,0]
	v_pk_mul_f32 v[28:29], v[28:29], v[82:83] op_sel_hi:[1,0]
	v_subrev_u32_e32 v32, s6, v130
	v_ashrrev_i32_e32 v33, 31, v32
	v_pk_mul_f32 v[26:27], v[26:27], v[82:83] op_sel_hi:[1,0]
	v_max_f32_e32 v24, 0, v24
	v_lshlrev_b64 v[32:33], 6, v[32:33]
	v_pk_mul_f32 v[30:31], v[30:31], v[82:83] op_sel_hi:[1,0]
	v_mul_f32_e32 v34, v24, v24
	v_max_f32_e32 v24, 0, v29
	v_max_f32_e32 v25, 0, v25
	v_max_f32_e32 v26, 0, v26
	v_lshl_add_u64 v[32:33], s[46:47], 0, v[32:33]
; __device__ __forceinline__ unsigned cvt_pk_bf16(float lo, float hi) { unsigned r; asm volatile("v_cvt_pk_bf16_f32 %0, %1, %2" : "=v"(r) : "v"(lo), "v"(hi)); return r; }
;     __device__ __forceinline__ void operator()(const f32x4 (&acc)[2][2][4][2], const Unit& u, int wr, int wc, int fr, int fq) const {
;     ...
;             for (int m = 0; m < 4; ++m) rsv[ai][m] = __builtin_amdgcn_rsqf(rsv[ai][m] * (1.0f / 1024.0f) + RMS_EPS);
; #pragma unroll
;         for (int ai = 0; ai < 2; ++ai)
; #pragma unroll
;             for (int m = 0; m < 4; ++m) {
;                 if (ai == 1 && !whole) continue;
;                 const int row = row0 + ai * HALF + m * 16;
;                 const float rs = rsv[ai][m];
;                 float s1 = 0.f, s2 = 0.f;
;                 bf16_t* rowp = BLK ? O + ((size_t)u.pm * (ldc >> 6) + (size_t)(col0 >> 6)) * 16384 + (size_t)((col0 >> 5) & 1) * 8192 + (size_t)(row - u.pm * BM) * 32 + (col0 & 31) : O + (size_t)row * ldc + col0;
; #pragma unroll
;                 for (int bj = 0; bj < 2; ++bj) {
;                     if (bj == 1 && !whole) continue;
;                     f32x4 v0 = acc[ai][bj][m][0] * rs, v1 = acc[ai][bj][m][1] * rs;
;                     if (ACT == 1) {
; #pragma unroll
;                         for (int j = 0; j < 4; ++j) { const float a = fmaxf(v0[j], 0.f), b = fmaxf(v1[j], 0.f); v0[j] = a * a; v1[j] = b * b; }
;                     }
;                     u32x4 w; w.x = cvt_pk_bf16(v0[0], v0[1]); w.y = cvt_pk_bf16(v0[2], v0[3]); w.z = cvt_pk_bf16(v1[0], v1[1]); w.w = cvt_pk_bf16(v1[2], v1[3]);
;                     *(u32x4*)(rowp + (BLK ? bj * 2 * 16384 : bj * HALF)) = w;
	v_max_f32_e32 v28, 0, v28
	v_mul_f32_e32 v24, v24, v24
	v_mul_f32_e32 v29, v25, v25
	v_max_f32_e32 v25, 0, v30
	v_mul_f32_e32 v30, v26, v26
	v_max_f32_e32 v26, 0, v31
	v_max_f32_e32 v27, 0, v27
	v_pk_mul_f32 v[16:17], v[16:17], v[82:83] op_sel_hi:[1,0]
	v_fmamk_f32 v72, v129, 0x3a800000, v211
	v_lshl_add_u64 v[32:33], v[32:33], 0, v[200:201]
	v_mul_f32_e32 v28, v28, v28
	v_mul_f32_e32 v25, v25, v25
	v_mul_f32_e32 v26, v26, v26
	v_mul_f32_e32 v27, v27, v27
	v_cvt_pk_bf16_f32 v24, v28, v24
	v_pk_mul_f32 v[20:21], v[20:21], v[82:83] op_sel_hi:[1,0]
	v_pk_mul_f32 v[18:19], v[18:19], v[82:83] op_sel_hi:[1,0]
	v_max_f32_e32 v16, 0, v16
	v_rsq_f32_e32 v72, v72
	v_cvt_pk_bf16_f32 v25, v25, v26
	v_cvt_pk_bf16_f32 v26, v34, v29
	v_cvt_pk_bf16_f32 v27, v30, v27
	global_store_dwordx4 v[32:33], v[24:27], off sc1
	v_pk_mul_f32 v[22:23], v[22:23], v[82:83] op_sel_hi:[1,0]
	v_max_f32_e32 v20, 0, v20
	v_mul_f32_e32 v24, v16, v16
	v_max_f32_e32 v16, 0, v21
	v_max_f32_e32 v17, 0, v17
	v_max_f32_e32 v18, 0, v18
	v_mul_f32_e32 v20, v20, v20
	v_mul_f32_e32 v16, v16, v16
	v_mul_f32_e32 v21, v17, v17
	v_max_f32_e32 v17, 0, v22
	v_mul_f32_e32 v22, v18, v18
	v_max_f32_e32 v18, 0, v23
	v_mul_f32_e32 v17, v17, v17
	v_max_f32_e32 v19, 0, v19
	v_mul_f32_e32 v18, v18, v18
	v_cvt_pk_bf16_f32 v16, v20, v16
	v_add_co_u32_e32 v20, vcc, s65, v32
	v_mul_f32_e32 v19, v19, v19
	v_cvt_pk_bf16_f32 v17, v17, v18
	v_cvt_pk_bf16_f32 v18, v24, v21
	s_nop 0
	v_addc_co_u32_e32 v21, vcc, 0, v33, vcc
	v_cvt_pk_bf16_f32 v19, v22, v19
	global_store_dwordx4 v[20:21], v[16:19], off sc1
	v_pk_mul_f32 v[8:9], v[8:9], v[72:73] op_sel_hi:[1,0]
	v_pk_mul_f32 v[12:13], v[12:13], v[72:73] op_sel_hi:[1,0]
	v_subrev_u32_e32 v16, s6, v128
	v_ashrrev_i32_e32 v17, 31, v16
	v_pk_mul_f32 v[10:11], v[10:11], v[72:73] op_sel_hi:[1,0]
	v_max_f32_e32 v8, 0, v8
	v_lshlrev_b64 v[16:17], 6, v[16:17]
	v_pk_mul_f32 v[14:15], v[14:15], v[72:73] op_sel_hi:[1,0]
	v_mul_f32_e32 v18, v8, v8
	v_max_f32_e32 v8, 0, v13
	v_max_f32_e32 v9, 0, v9
	v_max_f32_e32 v10, 0, v10
	v_lshl_add_u64 v[16:17], s[46:47], 0, v[16:17]
	v_max_f32_e32 v12, 0, v12
	v_mul_f32_e32 v8, v8, v8
	v_mul_f32_e32 v13, v9, v9
	v_max_f32_e32 v9, 0, v14
	v_mul_f32_e32 v14, v10, v10
	v_max_f32_e32 v10, 0, v15
	v_max_f32_e32 v11, 0, v11
	v_pk_mul_f32 v[0:1], v[0:1], v[72:73] op_sel_hi:[1,0]
	v_lshl_add_u64 v[16:17], v[16:17], 0, v[200:201]
	v_mul_f32_e32 v12, v12, v12
	v_mul_f32_e32 v9, v9, v9
	v_mul_f32_e32 v10, v10, v10
	v_mul_f32_e32 v11, v11, v11
	v_cvt_pk_bf16_f32 v8, v12, v8
	v_pk_mul_f32 v[4:5], v[4:5], v[72:73] op_sel_hi:[1,0]
	v_pk_mul_f32 v[2:3], v[2:3], v[72:73] op_sel_hi:[1,0]
	v_max_f32_e32 v0, 0, v0
	v_cvt_pk_bf16_f32 v9, v9, v10
	v_cvt_pk_bf16_f32 v10, v18, v13
	v_cvt_pk_bf16_f32 v11, v14, v11
	global_store_dwordx4 v[16:17], v[8:11], off sc1
	v_pk_mul_f32 v[6:7], v[6:7], v[72:73] op_sel_hi:[1,0]
	v_max_f32_e32 v4, 0, v4
	v_mul_f32_e32 v8, v0, v0
	v_max_f32_e32 v0, 0, v5
	v_max_f32_e32 v1, 0, v1
	v_max_f32_e32 v2, 0, v2
	v_mul_f32_e32 v4, v4, v4
	v_mul_f32_e32 v0, v0, v0
	v_mul_f32_e32 v5, v1, v1
	v_max_f32_e32 v1, 0, v6
	v_mul_f32_e32 v6, v2, v2
	v_max_f32_e32 v2, 0, v7
	v_mul_f32_e32 v1, v1, v1
	v_max_f32_e32 v3, 0, v3
	v_mul_f32_e32 v2, v2, v2
	v_cvt_pk_bf16_f32 v0, v4, v0
	v_add_co_u32_e32 v4, vcc, 0x10000, v16
	v_mul_f32_e32 v3, v3, v3
	v_cvt_pk_bf16_f32 v1, v1, v2
	v_cvt_pk_bf16_f32 v2, v8, v5
	s_nop 0
	v_addc_co_u32_e32 v5, vcc, 0, v17, vcc
	v_cvt_pk_bf16_f32 v3, v6, v3
	global_store_dwordx4 v[4:5], v[0:3], off sc1
	s_andn2_b64 vcc, exec, s[42:43]
	s_mov_b64 s[2:3], -1
	s_cbranch_vccnz .LBB0_1191
